# v71 with the k order alternating per accumulator tile in the GEMM MMA blocks (k0,k1 then k1,k0) so consecutive MFMAs across a tile boundary share one source operand register; f32 summation order insid
# baseline (speedup 1.0000x reference)
.LBB0_200:
	ds_read_b128 v[150:153], v161
	ds_read_b128 v[154:157], v161 offset:1024
	ds_read_b128 v[166:169], v161 offset:2048
	ds_read_b128 v[170:173], v161 offset:3072
	ds_read_b128 v[174:177], v162
	ds_read_b128 v[178:181], v162 offset:1024
	ds_read_b128 v[182:185], v162 offset:2048
	ds_read_b128 v[186:189], v162 offset:3072
	s_add_u32 s8, s55, s26
	s_addc_u32 s9, s63, 0
	s_cmp_eq_u32 s26, s4
	s_cselect_b32 s23, s0, s9
	s_cselect_b32 s22, s1, s8
	s_cselect_b32 s9, s41, s54
	s_cselect_b32 s8, s43, s53
	s_add_i32 s65, s18, 0xc000
	v_lshl_add_u64 v[144:145], v[2:3], 0, s[26:27]
	s_mov_b32 m0, s65
	s_add_i32 s64, s18, 0xe000
	ds_read_b128 v[190:193], v163
	ds_read_b128 v[194:197], v163 offset:1024
	ds_read_b128 v[198:201], v163 offset:2048
	ds_read_b128 v[202:205], v163 offset:3072
	ds_read_b128 v[206:209], v163 offset:4096
	ds_read_b128 v[210:213], v163 offset:5120
	ds_read_b128 v[214:217], v163 offset:6144
	ds_read_b128 v[218:221], v163 offset:7168
	global_load_lds_dwordx4 v[144:145], off
	s_mov_b32 m0, s64
	v_lshl_add_u64 v[144:145], v[148:149], 0, s[26:27]
	global_load_lds_dwordx4 v[144:145], off
	s_waitcnt vmcnt(8) lgkmcnt(0)
	s_barrier
	v_mfma_f32_16x16x32_bf16 v[128:131], v[150:153], v[190:193], v[128:131]
	v_mfma_f32_16x16x32_bf16 v[128:131], v[154:157], v[194:197], v[128:131]
	v_mfma_f32_16x16x32_bf16 v[124:127], v[170:173], v[194:197], v[124:127]
	v_mfma_f32_16x16x32_bf16 v[124:127], v[166:169], v[190:193], v[124:127]
	v_mfma_f32_16x16x32_bf16 v[108:111], v[166:169], v[198:201], v[108:111]
	v_mfma_f32_16x16x32_bf16 v[108:111], v[170:173], v[202:205], v[108:111]
	v_mfma_f32_16x16x32_bf16 v[112:115], v[154:157], v[202:205], v[112:115]
	v_mfma_f32_16x16x32_bf16 v[112:115], v[150:153], v[198:201], v[112:115]
	v_mfma_f32_16x16x32_bf16 v[96:99], v[150:153], v[206:209], v[96:99]
	v_mfma_f32_16x16x32_bf16 v[96:99], v[154:157], v[210:213], v[96:99]
	v_mfma_f32_16x16x32_bf16 v[92:95], v[170:173], v[210:213], v[92:95]
	v_mfma_f32_16x16x32_bf16 v[92:95], v[166:169], v[206:209], v[92:95]
	v_mfma_f32_16x16x32_bf16 v[76:79], v[166:169], v[214:217], v[76:79]
	v_mfma_f32_16x16x32_bf16 v[76:79], v[170:173], v[218:221], v[76:79]
	v_mfma_f32_16x16x32_bf16 v[80:83], v[154:157], v[218:221], v[80:83]
	v_mfma_f32_16x16x32_bf16 v[80:83], v[150:153], v[214:217], v[80:83]
	v_mfma_f32_16x16x32_bf16 v[72:75], v[174:177], v[214:217], v[72:75]
	v_mfma_f32_16x16x32_bf16 v[72:75], v[178:181], v[218:221], v[72:75]
	v_mfma_f32_16x16x32_bf16 v[68:71], v[186:189], v[218:221], v[68:71]
	v_mfma_f32_16x16x32_bf16 v[68:71], v[182:185], v[214:217], v[68:71]
	v_mfma_f32_16x16x32_bf16 v[84:87], v[182:185], v[206:209], v[84:87]
	v_mfma_f32_16x16x32_bf16 v[84:87], v[186:189], v[210:213], v[84:87]
	v_mfma_f32_16x16x32_bf16 v[88:91], v[178:181], v[210:213], v[88:91]
	v_mfma_f32_16x16x32_bf16 v[88:91], v[174:177], v[206:209], v[88:91]
	v_mfma_f32_16x16x32_bf16 v[104:107], v[174:177], v[198:201], v[104:107]
	v_mfma_f32_16x16x32_bf16 v[104:107], v[178:181], v[202:205], v[104:107]
	v_mfma_f32_16x16x32_bf16 v[100:103], v[186:189], v[202:205], v[100:103]
	v_mfma_f32_16x16x32_bf16 v[100:103], v[182:185], v[198:201], v[100:103]
	v_mfma_f32_16x16x32_bf16 v[116:119], v[182:185], v[190:193], v[116:119]
	v_mfma_f32_16x16x32_bf16 v[116:119], v[186:189], v[194:197], v[116:119]
	v_mfma_f32_16x16x32_bf16 v[120:123], v[178:181], v[194:197], v[120:123]
	v_mfma_f32_16x16x32_bf16 v[120:123], v[174:177], v[190:193], v[120:123]
	s_barrier
	s_add_i32 s12, s60, s17
	v_lshl_add_u64 v[144:145], s[8:9], 0, v[134:135]
	s_mov_b32 m0, s12
	ds_read_b128 v[190:193], v163 offset:16384
	ds_read_b128 v[194:197], v163 offset:17408
	ds_read_b128 v[198:201], v163 offset:18432
	ds_read_b128 v[202:205], v163 offset:19456
	ds_read_b128 v[206:209], v163 offset:20480
	ds_read_b128 v[210:213], v163 offset:21504
	ds_read_b128 v[214:217], v163 offset:22528
	ds_read_b128 v[218:221], v163 offset:23552
	global_load_lds_dwordx4 v[144:145], off
	s_add_i32 m0, s12, 0x2000
	s_add_u32 s12, s8, 0x4000
	v_lshl_add_u64 v[144:145], s[8:9], 0, v[138:139]
	s_addc_u32 s13, s9, 0
	s_add_i32 s14, s61, s17
	global_load_lds_dwordx4 v[144:145], off
	v_lshl_add_u64 v[144:145], s[12:13], 0, v[134:135]
	s_mov_b32 m0, s14
	v_lshl_add_u64 v[222:223], s[22:23], 0, v[136:137]
	global_load_lds_dwordx4 v[144:145], off
	s_add_i32 m0, s14, 0x2000
	v_lshl_add_u64 v[144:145], s[12:13], 0, v[138:139]
	global_load_lds_dwordx4 v[144:145], off
	s_mov_b32 m0, s18
	v_lshl_add_u64 v[144:145], s[22:23], 0, v[132:133]
	global_load_lds_dwordx4 v[144:145], off
	s_mov_b32 m0, s19
	s_nop 0
	global_load_lds_dwordx4 v[222:223], off
	s_waitcnt vmcnt(8) lgkmcnt(0)
	s_barrier
	v_mfma_f32_16x16x32_bf16 v[64:67], v[150:153], v[190:193], v[64:67]
	v_mfma_f32_16x16x32_bf16 v[64:67], v[154:157], v[194:197], v[64:67]
	v_mfma_f32_16x16x32_bf16 v[60:63], v[170:173], v[194:197], v[60:63]
	v_mfma_f32_16x16x32_bf16 v[60:63], v[166:169], v[190:193], v[60:63]
	v_mfma_f32_16x16x32_bf16 v[44:47], v[166:169], v[198:201], v[44:47]
	v_mfma_f32_16x16x32_bf16 v[44:47], v[170:173], v[202:205], v[44:47]
	v_mfma_f32_16x16x32_bf16 v[48:51], v[154:157], v[202:205], v[48:51]
	v_mfma_f32_16x16x32_bf16 v[48:51], v[150:153], v[198:201], v[48:51]
	v_mfma_f32_16x16x32_bf16 v[32:35], v[150:153], v[206:209], v[32:35]
	v_mfma_f32_16x16x32_bf16 v[32:35], v[154:157], v[210:213], v[32:35]
	v_mfma_f32_16x16x32_bf16 v[28:31], v[170:173], v[210:213], v[28:31]
	v_mfma_f32_16x16x32_bf16 v[28:31], v[166:169], v[206:209], v[28:31]
	v_mfma_f32_16x16x32_bf16 v[12:15], v[166:169], v[214:217], v[12:15]
	v_mfma_f32_16x16x32_bf16 v[12:15], v[170:173], v[218:221], v[12:15]
	v_mfma_f32_16x16x32_bf16 v[16:19], v[154:157], v[218:221], v[16:19]
	v_mfma_f32_16x16x32_bf16 v[16:19], v[150:153], v[214:217], v[16:19]
	v_mfma_f32_16x16x32_bf16 v[8:11], v[174:177], v[214:217], v[8:11]
	v_mfma_f32_16x16x32_bf16 v[8:11], v[178:181], v[218:221], v[8:11]
	v_mfma_f32_16x16x32_bf16 v[4:7], v[186:189], v[218:221], v[4:7]
	v_mfma_f32_16x16x32_bf16 v[4:7], v[182:185], v[214:217], v[4:7]
	v_mfma_f32_16x16x32_bf16 v[20:23], v[182:185], v[206:209], v[20:23]
	v_mfma_f32_16x16x32_bf16 v[20:23], v[186:189], v[210:213], v[20:23]
	v_mfma_f32_16x16x32_bf16 v[24:27], v[178:181], v[210:213], v[24:27]
	v_mfma_f32_16x16x32_bf16 v[24:27], v[174:177], v[206:209], v[24:27]
	v_mfma_f32_16x16x32_bf16 v[40:43], v[174:177], v[198:201], v[40:43]
	v_mfma_f32_16x16x32_bf16 v[40:43], v[178:181], v[202:205], v[40:43]
	v_mfma_f32_16x16x32_bf16 v[36:39], v[186:189], v[202:205], v[36:39]
	v_mfma_f32_16x16x32_bf16 v[36:39], v[182:185], v[198:201], v[36:39]
	v_mfma_f32_16x16x32_bf16 v[52:55], v[182:185], v[190:193], v[52:55]
	v_mfma_f32_16x16x32_bf16 v[52:55], v[186:189], v[194:197], v[52:55]
	v_mfma_f32_16x16x32_bf16 v[56:59], v[178:181], v[194:197], v[56:59]
	v_mfma_f32_16x16x32_bf16 v[56:59], v[174:177], v[190:193], v[56:59]
	s_barrier
	s_add_i32 s14, 0, 0x18000
	v_add_u32_e32 v1, s14, v160
	s_add_i32 s66, 0, 0x1c000
	ds_read_b128 v[150:153], v1
	ds_read_b128 v[154:157], v1 offset:1024
	ds_read_b128 v[166:169], v1 offset:2048
	ds_read_b128 v[170:173], v1 offset:3072
	v_add_u32_e32 v1, s66, v160
	ds_read_b128 v[174:177], v1
	ds_read_b128 v[178:181], v1 offset:1024
	ds_read_b128 v[182:185], v1 offset:2048
	ds_read_b128 v[186:189], v1 offset:3072
	s_add_u32 s12, s22, 0x100000
	s_addc_u32 s13, s23, 0
	s_mov_b32 m0, s20
	v_lshl_add_u64 v[224:225], s[12:13], 0, v[132:133]
	ds_read_b128 v[190:193], v163 offset:32768
	ds_read_b128 v[194:197], v163 offset:33792
	ds_read_b128 v[198:201], v163 offset:34816
	ds_read_b128 v[202:205], v163 offset:35840
	ds_read_b128 v[206:209], v163 offset:36864
	ds_read_b128 v[210:213], v163 offset:37888
	ds_read_b128 v[214:217], v163 offset:38912
	ds_read_b128 v[218:221], v163 offset:39936
	global_load_lds_dwordx4 v[224:225], off
	s_mov_b32 m0, s21
	v_lshl_add_u64 v[224:225], s[12:13], 0, v[136:137]
	global_load_lds_dwordx4 v[224:225], off
	s_waitcnt vmcnt(8) lgkmcnt(0)
	s_barrier
	v_mfma_f32_16x16x32_bf16 v[128:131], v[150:153], v[190:193], v[128:131]
	v_mfma_f32_16x16x32_bf16 v[128:131], v[154:157], v[194:197], v[128:131]
	v_mfma_f32_16x16x32_bf16 v[124:127], v[170:173], v[194:197], v[124:127]
	v_mfma_f32_16x16x32_bf16 v[124:127], v[166:169], v[190:193], v[124:127]
	v_mfma_f32_16x16x32_bf16 v[108:111], v[166:169], v[198:201], v[108:111]
	v_mfma_f32_16x16x32_bf16 v[108:111], v[170:173], v[202:205], v[108:111]
	v_mfma_f32_16x16x32_bf16 v[112:115], v[154:157], v[202:205], v[112:115]
	v_mfma_f32_16x16x32_bf16 v[112:115], v[150:153], v[198:201], v[112:115]
	v_mfma_f32_16x16x32_bf16 v[96:99], v[150:153], v[206:209], v[96:99]
	v_mfma_f32_16x16x32_bf16 v[96:99], v[154:157], v[210:213], v[96:99]
	v_mfma_f32_16x16x32_bf16 v[92:95], v[170:173], v[210:213], v[92:95]
	v_mfma_f32_16x16x32_bf16 v[92:95], v[166:169], v[206:209], v[92:95]
	v_mfma_f32_16x16x32_bf16 v[76:79], v[166:169], v[214:217], v[76:79]
	v_mfma_f32_16x16x32_bf16 v[76:79], v[170:173], v[218:221], v[76:79]
	v_mfma_f32_16x16x32_bf16 v[80:83], v[154:157], v[218:221], v[80:83]
	v_mfma_f32_16x16x32_bf16 v[80:83], v[150:153], v[214:217], v[80:83]
	v_mfma_f32_16x16x32_bf16 v[72:75], v[174:177], v[214:217], v[72:75]
	v_mfma_f32_16x16x32_bf16 v[72:75], v[178:181], v[218:221], v[72:75]
	v_mfma_f32_16x16x32_bf16 v[68:71], v[186:189], v[218:221], v[68:71]
	v_mfma_f32_16x16x32_bf16 v[68:71], v[182:185], v[214:217], v[68:71]
	v_mfma_f32_16x16x32_bf16 v[84:87], v[182:185], v[206:209], v[84:87]
	v_mfma_f32_16x16x32_bf16 v[84:87], v[186:189], v[210:213], v[84:87]
	v_mfma_f32_16x16x32_bf16 v[88:91], v[178:181], v[210:213], v[88:91]
	v_mfma_f32_16x16x32_bf16 v[88:91], v[174:177], v[206:209], v[88:91]
	v_mfma_f32_16x16x32_bf16 v[104:107], v[174:177], v[198:201], v[104:107]
	v_mfma_f32_16x16x32_bf16 v[104:107], v[178:181], v[202:205], v[104:107]
	v_mfma_f32_16x16x32_bf16 v[100:103], v[186:189], v[202:205], v[100:103]
	v_mfma_f32_16x16x32_bf16 v[100:103], v[182:185], v[198:201], v[100:103]
	v_mfma_f32_16x16x32_bf16 v[116:119], v[182:185], v[190:193], v[116:119]
	v_mfma_f32_16x16x32_bf16 v[116:119], v[186:189], v[194:197], v[116:119]
	v_mfma_f32_16x16x32_bf16 v[120:123], v[178:181], v[194:197], v[120:123]
	v_mfma_f32_16x16x32_bf16 v[120:123], v[174:177], v[190:193], v[120:123]
	s_barrier
	s_add_u32 s12, s8, 0x8000
	s_addc_u32 s13, s9, 0
	s_add_i32 s14, s14, s17
	v_lshl_add_u64 v[224:225], s[12:13], 0, v[134:135]
	s_mov_b32 m0, s14
	ds_read_b128 v[190:193], v163 offset:49152
	ds_read_b128 v[194:197], v163 offset:50176
	ds_read_b128 v[198:201], v163 offset:51200
	ds_read_b128 v[202:205], v163 offset:52224
	ds_read_b128 v[206:209], v163 offset:53248
	ds_read_b128 v[210:213], v163 offset:54272
	ds_read_b128 v[214:217], v163 offset:55296
	ds_read_b128 v[218:221], v163 offset:56320
	global_load_lds_dwordx4 v[224:225], off
	s_add_i32 m0, s14, 0x2000
	s_add_u32 s8, s8, 0xc000
	v_lshl_add_u64 v[224:225], s[12:13], 0, v[138:139]
	s_addc_u32 s9, s9, 0
	s_add_i32 s12, s66, s17
	global_load_lds_dwordx4 v[224:225], off
	v_lshl_add_u64 v[224:225], s[8:9], 0, v[134:135]
	s_mov_b32 m0, s12
	v_lshl_add_u64 v[144:145], v[144:145], 0, s[30:31]
	global_load_lds_dwordx4 v[224:225], off
	s_add_i32 m0, s12, 0x2000
	v_lshl_add_u64 v[224:225], s[8:9], 0, v[138:139]
	global_load_lds_dwordx4 v[224:225], off
	s_mov_b32 m0, s51
	s_nop 0
	global_load_lds_dwordx4 v[144:145], off
	s_mov_b32 m0, s56
	v_lshl_add_u64 v[144:145], v[222:223], 0, s[30:31]
	global_load_lds_dwordx4 v[144:145], off
	s_waitcnt vmcnt(8) lgkmcnt(0)
	s_barrier
	v_mfma_f32_16x16x32_bf16 v[64:67], v[150:153], v[190:193], v[64:67]
	v_mfma_f32_16x16x32_bf16 v[64:67], v[154:157], v[194:197], v[64:67]
	v_mfma_f32_16x16x32_bf16 v[60:63], v[170:173], v[194:197], v[60:63]
	v_mfma_f32_16x16x32_bf16 v[60:63], v[166:169], v[190:193], v[60:63]
	v_mfma_f32_16x16x32_bf16 v[44:47], v[166:169], v[198:201], v[44:47]
	v_mfma_f32_16x16x32_bf16 v[44:47], v[170:173], v[202:205], v[44:47]
	v_mfma_f32_16x16x32_bf16 v[48:51], v[154:157], v[202:205], v[48:51]
	v_mfma_f32_16x16x32_bf16 v[48:51], v[150:153], v[198:201], v[48:51]
	v_mfma_f32_16x16x32_bf16 v[32:35], v[150:153], v[206:209], v[32:35]
	v_mfma_f32_16x16x32_bf16 v[32:35], v[154:157], v[210:213], v[32:35]
	v_mfma_f32_16x16x32_bf16 v[28:31], v[170:173], v[210:213], v[28:31]
	v_mfma_f32_16x16x32_bf16 v[28:31], v[166:169], v[206:209], v[28:31]
	v_mfma_f32_16x16x32_bf16 v[12:15], v[166:169], v[214:217], v[12:15]
	v_mfma_f32_16x16x32_bf16 v[12:15], v[170:173], v[218:221], v[12:15]
	v_mfma_f32_16x16x32_bf16 v[16:19], v[154:157], v[218:221], v[16:19]
	v_mfma_f32_16x16x32_bf16 v[16:19], v[150:153], v[214:217], v[16:19]
	v_mfma_f32_16x16x32_bf16 v[8:11], v[174:177], v[214:217], v[8:11]
	v_mfma_f32_16x16x32_bf16 v[8:11], v[178:181], v[218:221], v[8:11]
	v_mfma_f32_16x16x32_bf16 v[4:7], v[186:189], v[218:221], v[4:7]
	v_mfma_f32_16x16x32_bf16 v[4:7], v[182:185], v[214:217], v[4:7]
	v_mfma_f32_16x16x32_bf16 v[20:23], v[182:185], v[206:209], v[20:23]
	v_mfma_f32_16x16x32_bf16 v[20:23], v[186:189], v[210:213], v[20:23]
	v_mfma_f32_16x16x32_bf16 v[24:27], v[178:181], v[210:213], v[24:27]
	v_mfma_f32_16x16x32_bf16 v[24:27], v[174:177], v[206:209], v[24:27]
	v_mfma_f32_16x16x32_bf16 v[40:43], v[174:177], v[198:201], v[40:43]
	v_mfma_f32_16x16x32_bf16 v[40:43], v[178:181], v[202:205], v[40:43]
	v_mfma_f32_16x16x32_bf16 v[36:39], v[186:189], v[202:205], v[36:39]
	v_mfma_f32_16x16x32_bf16 v[36:39], v[182:185], v[198:201], v[36:39]
	v_mfma_f32_16x16x32_bf16 v[52:55], v[182:185], v[190:193], v[52:55]
	v_mfma_f32_16x16x32_bf16 v[52:55], v[186:189], v[194:197], v[52:55]
	v_mfma_f32_16x16x32_bf16 v[56:59], v[178:181], v[194:197], v[56:59]
	v_mfma_f32_16x16x32_bf16 v[56:59], v[174:177], v[190:193], v[56:59]
	s_barrier
	s_add_i32 s52, s52, 2
	s_add_u32 s53, s53, 0x10000
	s_addc_u32 s54, s54, 0
	s_add_u32 s55, s55, 0x100
	s_addc_u32 s63, s63, 0
	s_add_u32 s4, s4, 0xffffff00
	s_addc_u32 s5, s5, -1
	v_lshl_add_u64 v[2:3], v[2:3], 0, s[36:37]
	s_cmp_gt_u32 s52, 61
	v_lshl_add_u64 v[148:149], v[148:149], 0, s[36:37]
	s_cbranch_scc0 .LBB0_200
	s_and_b64 vcc, exec, s[34:35]
	s_cbranch_vccz .LBB0_203
	s_barrier

.LBB0_510:
	ds_read_b128 v[158:161], v153
	ds_read_b128 v[162:165], v153 offset:1024
	ds_read_b128 v[166:169], v153 offset:2048
	ds_read_b128 v[170:173], v153 offset:3072
	ds_read_b128 v[174:177], v154
	ds_read_b128 v[178:181], v154 offset:1024
	ds_read_b128 v[182:185], v154 offset:2048
	ds_read_b128 v[186:189], v154 offset:3072
	s_add_u32 s12, s64, s26
	s_addc_u32 s13, s65, 0
	s_cmp_eq_u32 s26, s8
	s_cselect_b32 s23, s0, s13
	s_cselect_b32 s22, s1, s12
	s_cselect_b32 s57, s45, s63
	s_cselect_b32 s56, s47, s62
	s_add_i32 s67, s18, 0xc000
	v_lshl_add_u64 v[144:145], v[2:3], 0, s[26:27]
	s_mov_b32 m0, s67
	s_add_i32 s66, s18, 0xe000
	ds_read_b128 v[190:193], v155
	ds_read_b128 v[194:197], v155 offset:1024
	ds_read_b128 v[198:201], v155 offset:2048
	ds_read_b128 v[202:205], v155 offset:3072
	ds_read_b128 v[206:209], v155 offset:4096
	ds_read_b128 v[210:213], v155 offset:5120
	ds_read_b128 v[214:217], v155 offset:6144
	ds_read_b128 v[218:221], v155 offset:7168
	global_load_lds_dwordx4 v[144:145], off
	s_mov_b32 m0, s66
	v_lshl_add_u64 v[144:145], v[148:149], 0, s[26:27]
	global_load_lds_dwordx4 v[144:145], off
	s_waitcnt vmcnt(8) lgkmcnt(0)
	s_barrier
	v_mfma_f32_16x16x32_bf16 v[128:131], v[158:161], v[190:193], v[128:131]
	v_mfma_f32_16x16x32_bf16 v[128:131], v[162:165], v[194:197], v[128:131]
	v_mfma_f32_16x16x32_bf16 v[116:119], v[170:173], v[194:197], v[116:119]
	v_mfma_f32_16x16x32_bf16 v[116:119], v[166:169], v[190:193], v[116:119]
	v_mfma_f32_16x16x32_bf16 v[100:103], v[166:169], v[198:201], v[100:103]
	v_mfma_f32_16x16x32_bf16 v[100:103], v[170:173], v[202:205], v[100:103]
	v_mfma_f32_16x16x32_bf16 v[112:115], v[162:165], v[202:205], v[112:115]
	v_mfma_f32_16x16x32_bf16 v[112:115], v[158:161], v[198:201], v[112:115]
	v_mfma_f32_16x16x32_bf16 v[96:99], v[158:161], v[206:209], v[96:99]
	v_mfma_f32_16x16x32_bf16 v[96:99], v[162:165], v[210:213], v[96:99]
	v_mfma_f32_16x16x32_bf16 v[84:87], v[170:173], v[210:213], v[84:87]
	v_mfma_f32_16x16x32_bf16 v[84:87], v[166:169], v[206:209], v[84:87]
	v_mfma_f32_16x16x32_bf16 v[64:67], v[166:169], v[214:217], v[64:67]
	v_mfma_f32_16x16x32_bf16 v[64:67], v[170:173], v[218:221], v[64:67]
	v_mfma_f32_16x16x32_bf16 v[80:83], v[162:165], v[218:221], v[80:83]
	v_mfma_f32_16x16x32_bf16 v[80:83], v[158:161], v[214:217], v[80:83]
	v_mfma_f32_16x16x32_bf16 v[72:75], v[174:177], v[214:217], v[72:75]
	v_mfma_f32_16x16x32_bf16 v[72:75], v[178:181], v[218:221], v[72:75]
	v_mfma_f32_16x16x32_bf16 v[68:71], v[186:189], v[218:221], v[68:71]
	v_mfma_f32_16x16x32_bf16 v[68:71], v[182:185], v[214:217], v[68:71]
	v_mfma_f32_16x16x32_bf16 v[88:91], v[182:185], v[206:209], v[88:91]
	v_mfma_f32_16x16x32_bf16 v[88:91], v[186:189], v[210:213], v[88:91]
	v_mfma_f32_16x16x32_bf16 v[92:95], v[178:181], v[210:213], v[92:95]
	v_mfma_f32_16x16x32_bf16 v[92:95], v[174:177], v[206:209], v[92:95]
	v_mfma_f32_16x16x32_bf16 v[108:111], v[174:177], v[198:201], v[108:111]
	v_mfma_f32_16x16x32_bf16 v[108:111], v[178:181], v[202:205], v[108:111]
	v_mfma_f32_16x16x32_bf16 v[104:107], v[186:189], v[202:205], v[104:107]
	v_mfma_f32_16x16x32_bf16 v[104:107], v[182:185], v[198:201], v[104:107]
	v_mfma_f32_16x16x32_bf16 v[120:123], v[182:185], v[190:193], v[120:123]
	v_mfma_f32_16x16x32_bf16 v[120:123], v[186:189], v[194:197], v[120:123]
	v_mfma_f32_16x16x32_bf16 v[124:127], v[178:181], v[194:197], v[124:127]
	v_mfma_f32_16x16x32_bf16 v[124:127], v[174:177], v[190:193], v[124:127]
	s_barrier
	s_add_i32 s12, s58, s17
	v_lshl_add_u64 v[144:145], s[56:57], 0, v[134:135]
	s_mov_b32 m0, s12
	ds_read_b128 v[190:193], v155 offset:16384
	ds_read_b128 v[194:197], v155 offset:17408
	ds_read_b128 v[198:201], v155 offset:18432
	ds_read_b128 v[202:205], v155 offset:19456
	ds_read_b128 v[206:209], v155 offset:20480
	ds_read_b128 v[210:213], v155 offset:21504
	ds_read_b128 v[214:217], v155 offset:22528
	ds_read_b128 v[218:221], v155 offset:23552
	global_load_lds_dwordx4 v[144:145], off
	s_add_i32 m0, s12, 0x2000
	s_add_u32 s12, s56, 0x4000
	v_lshl_add_u64 v[144:145], s[56:57], 0, v[138:139]
	s_addc_u32 s13, s57, 0
	s_add_i32 s14, s59, s17
	global_load_lds_dwordx4 v[144:145], off
	v_lshl_add_u64 v[144:145], s[12:13], 0, v[134:135]
	s_mov_b32 m0, s14
	v_lshl_add_u64 v[222:223], s[22:23], 0, v[136:137]
	global_load_lds_dwordx4 v[144:145], off
	s_add_i32 m0, s14, 0x2000
	v_lshl_add_u64 v[144:145], s[12:13], 0, v[138:139]
	global_load_lds_dwordx4 v[144:145], off
	s_mov_b32 m0, s18
	v_lshl_add_u64 v[144:145], s[22:23], 0, v[132:133]
	global_load_lds_dwordx4 v[144:145], off
	s_mov_b32 m0, s19
	s_nop 0
	global_load_lds_dwordx4 v[222:223], off
	s_waitcnt vmcnt(8) lgkmcnt(0)
	s_barrier
	v_mfma_f32_16x16x32_bf16 v[76:79], v[158:161], v[190:193], v[76:79]
	v_mfma_f32_16x16x32_bf16 v[76:79], v[162:165], v[194:197], v[76:79]
	v_mfma_f32_16x16x32_bf16 v[52:55], v[170:173], v[194:197], v[52:55]
	v_mfma_f32_16x16x32_bf16 v[52:55], v[166:169], v[190:193], v[52:55]
	v_mfma_f32_16x16x32_bf16 v[36:39], v[166:169], v[198:201], v[36:39]
	v_mfma_f32_16x16x32_bf16 v[36:39], v[170:173], v[202:205], v[36:39]
	v_mfma_f32_16x16x32_bf16 v[48:51], v[162:165], v[202:205], v[48:51]
	v_mfma_f32_16x16x32_bf16 v[48:51], v[158:161], v[198:201], v[48:51]
	v_mfma_f32_16x16x32_bf16 v[32:35], v[158:161], v[206:209], v[32:35]
	v_mfma_f32_16x16x32_bf16 v[32:35], v[162:165], v[210:213], v[32:35]
	v_mfma_f32_16x16x32_bf16 v[20:23], v[170:173], v[210:213], v[20:23]
	v_mfma_f32_16x16x32_bf16 v[20:23], v[166:169], v[206:209], v[20:23]
	v_mfma_f32_16x16x32_bf16 v[4:7], v[166:169], v[214:217], v[4:7]
	v_mfma_f32_16x16x32_bf16 v[4:7], v[170:173], v[218:221], v[4:7]
	v_mfma_f32_16x16x32_bf16 v[16:19], v[162:165], v[218:221], v[16:19]
	v_mfma_f32_16x16x32_bf16 v[16:19], v[158:161], v[214:217], v[16:19]
	v_mfma_f32_16x16x32_bf16 v[12:15], v[174:177], v[214:217], v[12:15]
	v_mfma_f32_16x16x32_bf16 v[12:15], v[178:181], v[218:221], v[12:15]
	v_mfma_f32_16x16x32_bf16 v[8:11], v[186:189], v[218:221], v[8:11]
	v_mfma_f32_16x16x32_bf16 v[8:11], v[182:185], v[214:217], v[8:11]
	v_mfma_f32_16x16x32_bf16 v[24:27], v[182:185], v[206:209], v[24:27]
	v_mfma_f32_16x16x32_bf16 v[24:27], v[186:189], v[210:213], v[24:27]
	v_mfma_f32_16x16x32_bf16 v[28:31], v[178:181], v[210:213], v[28:31]
	v_mfma_f32_16x16x32_bf16 v[28:31], v[174:177], v[206:209], v[28:31]
	v_mfma_f32_16x16x32_bf16 v[44:47], v[174:177], v[198:201], v[44:47]
	v_mfma_f32_16x16x32_bf16 v[44:47], v[178:181], v[202:205], v[44:47]
	v_mfma_f32_16x16x32_bf16 v[40:43], v[186:189], v[202:205], v[40:43]
	v_mfma_f32_16x16x32_bf16 v[40:43], v[182:185], v[198:201], v[40:43]
	v_mfma_f32_16x16x32_bf16 v[56:59], v[182:185], v[190:193], v[56:59]
	v_mfma_f32_16x16x32_bf16 v[56:59], v[186:189], v[194:197], v[56:59]
	v_mfma_f32_16x16x32_bf16 v[60:63], v[178:181], v[194:197], v[60:63]
	v_mfma_f32_16x16x32_bf16 v[60:63], v[174:177], v[190:193], v[60:63]
	s_barrier
	s_add_i32 s14, 0, 0x18000
	v_add_u32_e32 v1, s14, v151
	s_add_i32 s68, 0, 0x1c000
	ds_read_b128 v[158:161], v1
	ds_read_b128 v[162:165], v1 offset:1024
	ds_read_b128 v[166:169], v1 offset:2048
	ds_read_b128 v[170:173], v1 offset:3072
	v_add_u32_e32 v1, s68, v151
	ds_read_b128 v[174:177], v1
	ds_read_b128 v[178:181], v1 offset:1024
	ds_read_b128 v[182:185], v1 offset:2048
	ds_read_b128 v[186:189], v1 offset:3072
	s_add_u32 s12, s22, 0x100000
	s_addc_u32 s13, s23, 0
	s_mov_b32 m0, s20
	v_lshl_add_u64 v[224:225], s[12:13], 0, v[132:133]
	ds_read_b128 v[190:193], v155 offset:32768
	ds_read_b128 v[194:197], v155 offset:33792
	ds_read_b128 v[198:201], v155 offset:34816
	ds_read_b128 v[202:205], v155 offset:35840
	ds_read_b128 v[206:209], v155 offset:36864
	ds_read_b128 v[210:213], v155 offset:37888
	ds_read_b128 v[214:217], v155 offset:38912
	ds_read_b128 v[218:221], v155 offset:39936
	global_load_lds_dwordx4 v[224:225], off
	s_mov_b32 m0, s21
	v_lshl_add_u64 v[224:225], s[12:13], 0, v[136:137]
	global_load_lds_dwordx4 v[224:225], off
	s_waitcnt vmcnt(8) lgkmcnt(0)
	s_barrier
	v_mfma_f32_16x16x32_bf16 v[128:131], v[158:161], v[190:193], v[128:131]
	v_mfma_f32_16x16x32_bf16 v[128:131], v[162:165], v[194:197], v[128:131]
	v_mfma_f32_16x16x32_bf16 v[116:119], v[170:173], v[194:197], v[116:119]
	v_mfma_f32_16x16x32_bf16 v[116:119], v[166:169], v[190:193], v[116:119]
	v_mfma_f32_16x16x32_bf16 v[100:103], v[166:169], v[198:201], v[100:103]
	v_mfma_f32_16x16x32_bf16 v[100:103], v[170:173], v[202:205], v[100:103]
	v_mfma_f32_16x16x32_bf16 v[112:115], v[162:165], v[202:205], v[112:115]
	v_mfma_f32_16x16x32_bf16 v[112:115], v[158:161], v[198:201], v[112:115]
	v_mfma_f32_16x16x32_bf16 v[96:99], v[158:161], v[206:209], v[96:99]
	v_mfma_f32_16x16x32_bf16 v[96:99], v[162:165], v[210:213], v[96:99]
	v_mfma_f32_16x16x32_bf16 v[84:87], v[170:173], v[210:213], v[84:87]
	v_mfma_f32_16x16x32_bf16 v[84:87], v[166:169], v[206:209], v[84:87]
	v_mfma_f32_16x16x32_bf16 v[64:67], v[166:169], v[214:217], v[64:67]
	v_mfma_f32_16x16x32_bf16 v[64:67], v[170:173], v[218:221], v[64:67]
	v_mfma_f32_16x16x32_bf16 v[80:83], v[162:165], v[218:221], v[80:83]
	v_mfma_f32_16x16x32_bf16 v[80:83], v[158:161], v[214:217], v[80:83]
	v_mfma_f32_16x16x32_bf16 v[72:75], v[174:177], v[214:217], v[72:75]
	v_mfma_f32_16x16x32_bf16 v[72:75], v[178:181], v[218:221], v[72:75]
	v_mfma_f32_16x16x32_bf16 v[68:71], v[186:189], v[218:221], v[68:71]
	v_mfma_f32_16x16x32_bf16 v[68:71], v[182:185], v[214:217], v[68:71]
	v_mfma_f32_16x16x32_bf16 v[88:91], v[182:185], v[206:209], v[88:91]
	v_mfma_f32_16x16x32_bf16 v[88:91], v[186:189], v[210:213], v[88:91]
	v_mfma_f32_16x16x32_bf16 v[92:95], v[178:181], v[210:213], v[92:95]
	v_mfma_f32_16x16x32_bf16 v[92:95], v[174:177], v[206:209], v[92:95]
	v_mfma_f32_16x16x32_bf16 v[108:111], v[174:177], v[198:201], v[108:111]
	v_mfma_f32_16x16x32_bf16 v[108:111], v[178:181], v[202:205], v[108:111]
	v_mfma_f32_16x16x32_bf16 v[104:107], v[186:189], v[202:205], v[104:107]
	v_mfma_f32_16x16x32_bf16 v[104:107], v[182:185], v[198:201], v[104:107]
	v_mfma_f32_16x16x32_bf16 v[120:123], v[182:185], v[190:193], v[120:123]
	v_mfma_f32_16x16x32_bf16 v[120:123], v[186:189], v[194:197], v[120:123]
	v_mfma_f32_16x16x32_bf16 v[124:127], v[178:181], v[194:197], v[124:127]
	v_mfma_f32_16x16x32_bf16 v[124:127], v[174:177], v[190:193], v[124:127]
	s_barrier
	s_add_u32 s12, s56, 0x8000
	s_addc_u32 s13, s57, 0
	s_add_i32 s14, s14, s17
	v_lshl_add_u64 v[224:225], s[12:13], 0, v[134:135]
	s_mov_b32 m0, s14
	ds_read_b128 v[190:193], v155 offset:49152
	ds_read_b128 v[194:197], v155 offset:50176
	ds_read_b128 v[198:201], v155 offset:51200
	ds_read_b128 v[202:205], v155 offset:52224
	ds_read_b128 v[206:209], v155 offset:53248
	ds_read_b128 v[210:213], v155 offset:54272
	ds_read_b128 v[214:217], v155 offset:55296
	ds_read_b128 v[218:221], v155 offset:56320
	global_load_lds_dwordx4 v[224:225], off
	s_add_i32 m0, s14, 0x2000
	v_lshl_add_u64 v[224:225], s[12:13], 0, v[138:139]
	s_add_u32 s12, s56, 0xc000
	s_addc_u32 s13, s57, 0
	s_add_i32 s14, s68, s17
	global_load_lds_dwordx4 v[224:225], off
	v_lshl_add_u64 v[224:225], s[12:13], 0, v[134:135]
	s_mov_b32 m0, s14
	v_lshl_add_u64 v[144:145], v[144:145], 0, s[36:37]
	global_load_lds_dwordx4 v[224:225], off
	s_add_i32 m0, s14, 0x2000
	v_lshl_add_u64 v[224:225], s[12:13], 0, v[138:139]
	global_load_lds_dwordx4 v[224:225], off
	s_mov_b32 m0, s25
	s_nop 0
	global_load_lds_dwordx4 v[144:145], off
	s_mov_b32 m0, s33
	v_lshl_add_u64 v[144:145], v[222:223], 0, s[36:37]
	global_load_lds_dwordx4 v[144:145], off
	s_waitcnt vmcnt(8) lgkmcnt(0)
	s_barrier
	v_mfma_f32_16x16x32_bf16 v[76:79], v[158:161], v[190:193], v[76:79]
	v_mfma_f32_16x16x32_bf16 v[76:79], v[162:165], v[194:197], v[76:79]
	v_mfma_f32_16x16x32_bf16 v[52:55], v[170:173], v[194:197], v[52:55]
	v_mfma_f32_16x16x32_bf16 v[52:55], v[166:169], v[190:193], v[52:55]
	v_mfma_f32_16x16x32_bf16 v[36:39], v[166:169], v[198:201], v[36:39]
	v_mfma_f32_16x16x32_bf16 v[36:39], v[170:173], v[202:205], v[36:39]
	v_mfma_f32_16x16x32_bf16 v[48:51], v[162:165], v[202:205], v[48:51]
	v_mfma_f32_16x16x32_bf16 v[48:51], v[158:161], v[198:201], v[48:51]
	v_mfma_f32_16x16x32_bf16 v[32:35], v[158:161], v[206:209], v[32:35]
	v_mfma_f32_16x16x32_bf16 v[32:35], v[162:165], v[210:213], v[32:35]
	v_mfma_f32_16x16x32_bf16 v[20:23], v[170:173], v[210:213], v[20:23]
	v_mfma_f32_16x16x32_bf16 v[20:23], v[166:169], v[206:209], v[20:23]
	v_mfma_f32_16x16x32_bf16 v[4:7], v[166:169], v[214:217], v[4:7]
	v_mfma_f32_16x16x32_bf16 v[4:7], v[170:173], v[218:221], v[4:7]
	v_mfma_f32_16x16x32_bf16 v[16:19], v[162:165], v[218:221], v[16:19]
	v_mfma_f32_16x16x32_bf16 v[16:19], v[158:161], v[214:217], v[16:19]
	v_mfma_f32_16x16x32_bf16 v[12:15], v[174:177], v[214:217], v[12:15]
	v_mfma_f32_16x16x32_bf16 v[12:15], v[178:181], v[218:221], v[12:15]
	v_mfma_f32_16x16x32_bf16 v[8:11], v[186:189], v[218:221], v[8:11]
	v_mfma_f32_16x16x32_bf16 v[8:11], v[182:185], v[214:217], v[8:11]
	v_mfma_f32_16x16x32_bf16 v[24:27], v[182:185], v[206:209], v[24:27]
	v_mfma_f32_16x16x32_bf16 v[24:27], v[186:189], v[210:213], v[24:27]
	v_mfma_f32_16x16x32_bf16 v[28:31], v[178:181], v[210:213], v[28:31]
	v_mfma_f32_16x16x32_bf16 v[28:31], v[174:177], v[206:209], v[28:31]
	v_mfma_f32_16x16x32_bf16 v[44:47], v[174:177], v[198:201], v[44:47]
	v_mfma_f32_16x16x32_bf16 v[44:47], v[178:181], v[202:205], v[44:47]
	v_mfma_f32_16x16x32_bf16 v[40:43], v[186:189], v[202:205], v[40:43]
	v_mfma_f32_16x16x32_bf16 v[40:43], v[182:185], v[198:201], v[40:43]
	v_mfma_f32_16x16x32_bf16 v[56:59], v[182:185], v[190:193], v[56:59]
	v_mfma_f32_16x16x32_bf16 v[56:59], v[186:189], v[194:197], v[56:59]
	v_mfma_f32_16x16x32_bf16 v[60:63], v[178:181], v[194:197], v[60:63]
	v_mfma_f32_16x16x32_bf16 v[60:63], v[174:177], v[190:193], v[60:63]
	s_barrier
	s_add_i32 s61, s61, 2
	s_add_u32 s62, s62, 0x10000
	s_addc_u32 s63, s63, 0
	s_add_u32 s64, s64, 0x100
	s_addc_u32 s65, s65, 0
	s_add_u32 s8, s8, 0xffffff00
	s_addc_u32 s9, s9, -1
	v_lshl_add_u64 v[2:3], v[2:3], 0, s[40:41]
	s_cmp_gt_u32 s61, 61
	v_lshl_add_u64 v[148:149], v[148:149], 0, s[40:41]
	s_cbranch_scc0 .LBB0_510
	s_and_b64 vcc, exec, s[38:39]
	s_cbranch_vccz .LBB0_513
	s_barrier

.LBB0_668:
	ds_read_b128 v[158:161], v155
	ds_read_b128 v[162:165], v155 offset:1024
	ds_read_b128 v[166:169], v155 offset:2048
	ds_read_b128 v[170:173], v155 offset:3072
	ds_read_b128 v[174:177], v156
	ds_read_b128 v[178:181], v156 offset:1024
	ds_read_b128 v[182:185], v156 offset:2048
	ds_read_b128 v[186:189], v156 offset:3072
	s_add_u32 s12, s70, s34
	s_addc_u32 s13, s71, 0
	s_cmp_eq_u32 s34, s6
	s_cselect_b32 s23, s0, s13
	s_cselect_b32 s22, s1, s12
	s_cselect_b32 s55, s43, s69
	s_cselect_b32 s54, s66, s68
	s_add_i32 s73, s21, 0xc000
	v_lshl_add_u64 v[144:145], v[2:3], 0, s[34:35]
	s_mov_b32 m0, s73
	s_add_i32 s72, s21, 0xe000
	ds_read_b128 v[190:193], v157
	ds_read_b128 v[194:197], v157 offset:1024
	ds_read_b128 v[198:201], v157 offset:2048
	ds_read_b128 v[202:205], v157 offset:3072
	ds_read_b128 v[206:209], v157 offset:4096
	ds_read_b128 v[210:213], v157 offset:5120
	ds_read_b128 v[214:217], v157 offset:6144
	ds_read_b128 v[218:221], v157 offset:7168
	global_load_lds_dwordx4 v[144:145], off
	s_mov_b32 m0, s72
	v_lshl_add_u64 v[144:145], v[148:149], 0, s[34:35]
	global_load_lds_dwordx4 v[144:145], off
	s_waitcnt vmcnt(8) lgkmcnt(0)
	s_barrier
	v_mfma_f32_16x16x32_bf16 v[120:123], v[158:161], v[190:193], v[120:123]
	v_mfma_f32_16x16x32_bf16 v[120:123], v[162:165], v[194:197], v[120:123]
	v_mfma_f32_16x16x32_bf16 v[116:119], v[170:173], v[194:197], v[116:119]
	v_mfma_f32_16x16x32_bf16 v[116:119], v[166:169], v[190:193], v[116:119]
	v_mfma_f32_16x16x32_bf16 v[100:103], v[166:169], v[198:201], v[100:103]
	v_mfma_f32_16x16x32_bf16 v[100:103], v[170:173], v[202:205], v[100:103]
	v_mfma_f32_16x16x32_bf16 v[104:107], v[162:165], v[202:205], v[104:107]
	v_mfma_f32_16x16x32_bf16 v[104:107], v[158:161], v[198:201], v[104:107]
	v_mfma_f32_16x16x32_bf16 v[88:91], v[158:161], v[206:209], v[88:91]
	v_mfma_f32_16x16x32_bf16 v[88:91], v[162:165], v[210:213], v[88:91]
	v_mfma_f32_16x16x32_bf16 v[84:87], v[170:173], v[210:213], v[84:87]
	v_mfma_f32_16x16x32_bf16 v[84:87], v[166:169], v[206:209], v[84:87]
	v_mfma_f32_16x16x32_bf16 v[68:71], v[166:169], v[214:217], v[68:71]
	v_mfma_f32_16x16x32_bf16 v[68:71], v[170:173], v[218:221], v[68:71]
	v_mfma_f32_16x16x32_bf16 v[72:75], v[162:165], v[218:221], v[72:75]
	v_mfma_f32_16x16x32_bf16 v[72:75], v[158:161], v[214:217], v[72:75]
	v_mfma_f32_16x16x32_bf16 v[80:83], v[174:177], v[214:217], v[80:83]
	v_mfma_f32_16x16x32_bf16 v[80:83], v[178:181], v[218:221], v[80:83]
	v_mfma_f32_16x16x32_bf16 v[76:79], v[186:189], v[218:221], v[76:79]
	v_mfma_f32_16x16x32_bf16 v[76:79], v[182:185], v[214:217], v[76:79]
	v_mfma_f32_16x16x32_bf16 v[92:95], v[182:185], v[206:209], v[92:95]
	v_mfma_f32_16x16x32_bf16 v[92:95], v[186:189], v[210:213], v[92:95]
	v_mfma_f32_16x16x32_bf16 v[96:99], v[178:181], v[210:213], v[96:99]
	v_mfma_f32_16x16x32_bf16 v[96:99], v[174:177], v[206:209], v[96:99]
	v_mfma_f32_16x16x32_bf16 v[112:115], v[174:177], v[198:201], v[112:115]
	v_mfma_f32_16x16x32_bf16 v[112:115], v[178:181], v[202:205], v[112:115]
	v_mfma_f32_16x16x32_bf16 v[108:111], v[186:189], v[202:205], v[108:111]
	v_mfma_f32_16x16x32_bf16 v[108:111], v[182:185], v[198:201], v[108:111]
	v_mfma_f32_16x16x32_bf16 v[124:127], v[182:185], v[190:193], v[124:127]
	v_mfma_f32_16x16x32_bf16 v[124:127], v[186:189], v[194:197], v[124:127]
	v_mfma_f32_16x16x32_bf16 v[128:131], v[178:181], v[194:197], v[128:131]
	v_mfma_f32_16x16x32_bf16 v[128:131], v[174:177], v[190:193], v[128:131]
	s_barrier
	s_add_i32 s12, s58, s20
	v_lshl_add_u64 v[144:145], s[54:55], 0, v[134:135]
	s_mov_b32 m0, s12
	ds_read_b128 v[190:193], v157 offset:16384
	ds_read_b128 v[194:197], v157 offset:17408
	ds_read_b128 v[198:201], v157 offset:18432
	ds_read_b128 v[202:205], v157 offset:19456
	ds_read_b128 v[206:209], v157 offset:20480
	ds_read_b128 v[210:213], v157 offset:21504
	ds_read_b128 v[214:217], v157 offset:22528
	ds_read_b128 v[218:221], v157 offset:23552
	global_load_lds_dwordx4 v[144:145], off
	s_add_i32 m0, s12, 0x2000
	s_add_u32 s12, s54, 0x4000
	v_lshl_add_u64 v[144:145], s[54:55], 0, v[138:139]
	s_addc_u32 s13, s55, 0
	s_add_i32 s14, s59, s20
	global_load_lds_dwordx4 v[144:145], off
	v_lshl_add_u64 v[144:145], s[12:13], 0, v[134:135]
	s_mov_b32 m0, s14
	v_lshl_add_u64 v[222:223], s[22:23], 0, v[136:137]
	global_load_lds_dwordx4 v[144:145], off
	s_add_i32 m0, s14, 0x2000
	v_lshl_add_u64 v[144:145], s[12:13], 0, v[138:139]
	global_load_lds_dwordx4 v[144:145], off
	s_mov_b32 m0, s21
	v_lshl_add_u64 v[144:145], s[22:23], 0, v[132:133]
	global_load_lds_dwordx4 v[144:145], off
	s_mov_b32 m0, s24
	s_nop 0
	global_load_lds_dwordx4 v[222:223], off
	s_waitcnt vmcnt(8) lgkmcnt(0)
	s_barrier
	v_mfma_f32_16x16x32_bf16 v[56:59], v[158:161], v[190:193], v[56:59]
	v_mfma_f32_16x16x32_bf16 v[56:59], v[162:165], v[194:197], v[56:59]
	v_mfma_f32_16x16x32_bf16 v[52:55], v[170:173], v[194:197], v[52:55]
	v_mfma_f32_16x16x32_bf16 v[52:55], v[166:169], v[190:193], v[52:55]
	v_mfma_f32_16x16x32_bf16 v[36:39], v[166:169], v[198:201], v[36:39]
	v_mfma_f32_16x16x32_bf16 v[36:39], v[170:173], v[202:205], v[36:39]
	v_mfma_f32_16x16x32_bf16 v[40:43], v[162:165], v[202:205], v[40:43]
	v_mfma_f32_16x16x32_bf16 v[40:43], v[158:161], v[198:201], v[40:43]
	v_mfma_f32_16x16x32_bf16 v[24:27], v[158:161], v[206:209], v[24:27]
	v_mfma_f32_16x16x32_bf16 v[24:27], v[162:165], v[210:213], v[24:27]
	v_mfma_f32_16x16x32_bf16 v[20:23], v[170:173], v[210:213], v[20:23]
	v_mfma_f32_16x16x32_bf16 v[20:23], v[166:169], v[206:209], v[20:23]
	v_mfma_f32_16x16x32_bf16 v[4:7], v[166:169], v[214:217], v[4:7]
	v_mfma_f32_16x16x32_bf16 v[4:7], v[170:173], v[218:221], v[4:7]
	v_mfma_f32_16x16x32_bf16 v[8:11], v[162:165], v[218:221], v[8:11]
	v_mfma_f32_16x16x32_bf16 v[8:11], v[158:161], v[214:217], v[8:11]
	v_mfma_f32_16x16x32_bf16 v[16:19], v[174:177], v[214:217], v[16:19]
	v_mfma_f32_16x16x32_bf16 v[16:19], v[178:181], v[218:221], v[16:19]
	v_mfma_f32_16x16x32_bf16 v[12:15], v[186:189], v[218:221], v[12:15]
	v_mfma_f32_16x16x32_bf16 v[12:15], v[182:185], v[214:217], v[12:15]
	v_mfma_f32_16x16x32_bf16 v[28:31], v[182:185], v[206:209], v[28:31]
	v_mfma_f32_16x16x32_bf16 v[28:31], v[186:189], v[210:213], v[28:31]
	v_mfma_f32_16x16x32_bf16 v[32:35], v[178:181], v[210:213], v[32:35]
	v_mfma_f32_16x16x32_bf16 v[32:35], v[174:177], v[206:209], v[32:35]
	v_mfma_f32_16x16x32_bf16 v[48:51], v[174:177], v[198:201], v[48:51]
	v_mfma_f32_16x16x32_bf16 v[48:51], v[178:181], v[202:205], v[48:51]
	v_mfma_f32_16x16x32_bf16 v[44:47], v[186:189], v[202:205], v[44:47]
	v_mfma_f32_16x16x32_bf16 v[44:47], v[182:185], v[198:201], v[44:47]
	v_mfma_f32_16x16x32_bf16 v[60:63], v[182:185], v[190:193], v[60:63]
	v_mfma_f32_16x16x32_bf16 v[60:63], v[186:189], v[194:197], v[60:63]
	v_mfma_f32_16x16x32_bf16 v[64:67], v[178:181], v[194:197], v[64:67]
	v_mfma_f32_16x16x32_bf16 v[64:67], v[174:177], v[190:193], v[64:67]
	s_barrier
	s_add_i32 s14, 0, 0x18000
	v_add_u32_e32 v1, s14, v152
	s_add_i32 s74, 0, 0x1c000
	ds_read_b128 v[158:161], v1
	ds_read_b128 v[162:165], v1 offset:1024
	ds_read_b128 v[166:169], v1 offset:2048
	ds_read_b128 v[170:173], v1 offset:3072
	v_add_u32_e32 v1, s74, v152
	ds_read_b128 v[174:177], v1
	ds_read_b128 v[178:181], v1 offset:1024
	ds_read_b128 v[182:185], v1 offset:2048
	ds_read_b128 v[186:189], v1 offset:3072
	s_add_u32 s12, s22, 0x100000
	s_addc_u32 s13, s23, 0
	s_mov_b32 m0, s25
	v_lshl_add_u64 v[224:225], s[12:13], 0, v[132:133]
	ds_read_b128 v[190:193], v157 offset:32768
	ds_read_b128 v[194:197], v157 offset:33792
	ds_read_b128 v[198:201], v157 offset:34816
	ds_read_b128 v[202:205], v157 offset:35840
	ds_read_b128 v[206:209], v157 offset:36864
	ds_read_b128 v[210:213], v157 offset:37888
	ds_read_b128 v[214:217], v157 offset:38912
	ds_read_b128 v[218:221], v157 offset:39936
	global_load_lds_dwordx4 v[224:225], off
	s_mov_b32 m0, s33
	v_lshl_add_u64 v[224:225], s[12:13], 0, v[136:137]
	global_load_lds_dwordx4 v[224:225], off
	s_waitcnt vmcnt(8) lgkmcnt(0)
	s_barrier
	v_mfma_f32_16x16x32_bf16 v[120:123], v[158:161], v[190:193], v[120:123]
	v_mfma_f32_16x16x32_bf16 v[120:123], v[162:165], v[194:197], v[120:123]
	v_mfma_f32_16x16x32_bf16 v[116:119], v[170:173], v[194:197], v[116:119]
	v_mfma_f32_16x16x32_bf16 v[116:119], v[166:169], v[190:193], v[116:119]
	v_mfma_f32_16x16x32_bf16 v[100:103], v[166:169], v[198:201], v[100:103]
	v_mfma_f32_16x16x32_bf16 v[100:103], v[170:173], v[202:205], v[100:103]
	v_mfma_f32_16x16x32_bf16 v[104:107], v[162:165], v[202:205], v[104:107]
	v_mfma_f32_16x16x32_bf16 v[104:107], v[158:161], v[198:201], v[104:107]
	v_mfma_f32_16x16x32_bf16 v[88:91], v[158:161], v[206:209], v[88:91]
	v_mfma_f32_16x16x32_bf16 v[88:91], v[162:165], v[210:213], v[88:91]
	v_mfma_f32_16x16x32_bf16 v[84:87], v[170:173], v[210:213], v[84:87]
	v_mfma_f32_16x16x32_bf16 v[84:87], v[166:169], v[206:209], v[84:87]
	v_mfma_f32_16x16x32_bf16 v[68:71], v[166:169], v[214:217], v[68:71]
	v_mfma_f32_16x16x32_bf16 v[68:71], v[170:173], v[218:221], v[68:71]
	v_mfma_f32_16x16x32_bf16 v[72:75], v[162:165], v[218:221], v[72:75]
	v_mfma_f32_16x16x32_bf16 v[72:75], v[158:161], v[214:217], v[72:75]
	v_mfma_f32_16x16x32_bf16 v[80:83], v[174:177], v[214:217], v[80:83]
	v_mfma_f32_16x16x32_bf16 v[80:83], v[178:181], v[218:221], v[80:83]
	v_mfma_f32_16x16x32_bf16 v[76:79], v[186:189], v[218:221], v[76:79]
	v_mfma_f32_16x16x32_bf16 v[76:79], v[182:185], v[214:217], v[76:79]
	v_mfma_f32_16x16x32_bf16 v[92:95], v[182:185], v[206:209], v[92:95]
	v_mfma_f32_16x16x32_bf16 v[92:95], v[186:189], v[210:213], v[92:95]
	v_mfma_f32_16x16x32_bf16 v[96:99], v[178:181], v[210:213], v[96:99]
	v_mfma_f32_16x16x32_bf16 v[96:99], v[174:177], v[206:209], v[96:99]
	v_mfma_f32_16x16x32_bf16 v[112:115], v[174:177], v[198:201], v[112:115]
	v_mfma_f32_16x16x32_bf16 v[112:115], v[178:181], v[202:205], v[112:115]
	v_mfma_f32_16x16x32_bf16 v[108:111], v[186:189], v[202:205], v[108:111]
	v_mfma_f32_16x16x32_bf16 v[108:111], v[182:185], v[198:201], v[108:111]
	v_mfma_f32_16x16x32_bf16 v[124:127], v[182:185], v[190:193], v[124:127]
	v_mfma_f32_16x16x32_bf16 v[124:127], v[186:189], v[194:197], v[124:127]
	v_mfma_f32_16x16x32_bf16 v[128:131], v[178:181], v[194:197], v[128:131]
	v_mfma_f32_16x16x32_bf16 v[128:131], v[174:177], v[190:193], v[128:131]
	s_barrier
	s_add_u32 s12, s54, 0x8000
	s_addc_u32 s13, s55, 0
	s_add_i32 s14, s14, s20
	v_lshl_add_u64 v[224:225], s[12:13], 0, v[134:135]
	s_mov_b32 m0, s14
	ds_read_b128 v[190:193], v157 offset:49152
	ds_read_b128 v[194:197], v157 offset:50176
	ds_read_b128 v[198:201], v157 offset:51200
	ds_read_b128 v[202:205], v157 offset:52224
	ds_read_b128 v[206:209], v157 offset:53248
	ds_read_b128 v[210:213], v157 offset:54272
	ds_read_b128 v[214:217], v157 offset:55296
	ds_read_b128 v[218:221], v157 offset:56320
	global_load_lds_dwordx4 v[224:225], off
	s_add_i32 m0, s14, 0x2000
	v_lshl_add_u64 v[224:225], s[12:13], 0, v[138:139]
	s_add_u32 s12, s54, 0xc000
	s_addc_u32 s13, s55, 0
	s_add_i32 s14, s74, s20
	global_load_lds_dwordx4 v[224:225], off
	v_lshl_add_u64 v[224:225], s[12:13], 0, v[134:135]
	s_mov_b32 m0, s14
	v_lshl_add_u64 v[144:145], v[144:145], 0, s[30:31]
	global_load_lds_dwordx4 v[224:225], off
	s_add_i32 m0, s14, 0x2000
	v_lshl_add_u64 v[224:225], s[12:13], 0, v[138:139]
	global_load_lds_dwordx4 v[224:225], off
	s_mov_b32 m0, s51
	s_nop 0
	global_load_lds_dwordx4 v[144:145], off
	s_mov_b32 m0, s53
	v_lshl_add_u64 v[144:145], v[222:223], 0, s[30:31]
	global_load_lds_dwordx4 v[144:145], off
	s_waitcnt vmcnt(8) lgkmcnt(0)
	s_barrier
	v_mfma_f32_16x16x32_bf16 v[56:59], v[158:161], v[190:193], v[56:59]
	v_mfma_f32_16x16x32_bf16 v[56:59], v[162:165], v[194:197], v[56:59]
	v_mfma_f32_16x16x32_bf16 v[52:55], v[170:173], v[194:197], v[52:55]
	v_mfma_f32_16x16x32_bf16 v[52:55], v[166:169], v[190:193], v[52:55]
	v_mfma_f32_16x16x32_bf16 v[36:39], v[166:169], v[198:201], v[36:39]
	v_mfma_f32_16x16x32_bf16 v[36:39], v[170:173], v[202:205], v[36:39]
	v_mfma_f32_16x16x32_bf16 v[40:43], v[162:165], v[202:205], v[40:43]
	v_mfma_f32_16x16x32_bf16 v[40:43], v[158:161], v[198:201], v[40:43]
	v_mfma_f32_16x16x32_bf16 v[24:27], v[158:161], v[206:209], v[24:27]
	v_mfma_f32_16x16x32_bf16 v[24:27], v[162:165], v[210:213], v[24:27]
	v_mfma_f32_16x16x32_bf16 v[20:23], v[170:173], v[210:213], v[20:23]
	v_mfma_f32_16x16x32_bf16 v[20:23], v[166:169], v[206:209], v[20:23]
	v_mfma_f32_16x16x32_bf16 v[4:7], v[166:169], v[214:217], v[4:7]
	v_mfma_f32_16x16x32_bf16 v[4:7], v[170:173], v[218:221], v[4:7]
	v_mfma_f32_16x16x32_bf16 v[8:11], v[162:165], v[218:221], v[8:11]
	v_mfma_f32_16x16x32_bf16 v[8:11], v[158:161], v[214:217], v[8:11]
	v_mfma_f32_16x16x32_bf16 v[16:19], v[174:177], v[214:217], v[16:19]
	v_mfma_f32_16x16x32_bf16 v[16:19], v[178:181], v[218:221], v[16:19]
	v_mfma_f32_16x16x32_bf16 v[12:15], v[186:189], v[218:221], v[12:15]
	v_mfma_f32_16x16x32_bf16 v[12:15], v[182:185], v[214:217], v[12:15]
	v_mfma_f32_16x16x32_bf16 v[28:31], v[182:185], v[206:209], v[28:31]
	v_mfma_f32_16x16x32_bf16 v[28:31], v[186:189], v[210:213], v[28:31]
	v_mfma_f32_16x16x32_bf16 v[32:35], v[178:181], v[210:213], v[32:35]
	v_mfma_f32_16x16x32_bf16 v[32:35], v[174:177], v[206:209], v[32:35]
	v_mfma_f32_16x16x32_bf16 v[48:51], v[174:177], v[198:201], v[48:51]
	v_mfma_f32_16x16x32_bf16 v[48:51], v[178:181], v[202:205], v[48:51]
	v_mfma_f32_16x16x32_bf16 v[44:47], v[186:189], v[202:205], v[44:47]
	v_mfma_f32_16x16x32_bf16 v[44:47], v[182:185], v[198:201], v[44:47]
	v_mfma_f32_16x16x32_bf16 v[60:63], v[182:185], v[190:193], v[60:63]
	v_mfma_f32_16x16x32_bf16 v[60:63], v[186:189], v[194:197], v[60:63]
	v_mfma_f32_16x16x32_bf16 v[64:67], v[178:181], v[194:197], v[64:67]
	v_mfma_f32_16x16x32_bf16 v[64:67], v[174:177], v[190:193], v[64:67]
	s_barrier
	s_add_i32 s67, s67, 2
	s_add_u32 s68, s68, 0x10000
	s_addc_u32 s69, s69, 0
	s_add_u32 s70, s70, 0x100
	s_addc_u32 s71, s71, 0
	s_add_u32 s6, s6, 0xffffff00
	s_addc_u32 s7, s7, -1
	v_lshl_add_u64 v[2:3], v[2:3], 0, s[38:39]
	s_cmp_gt_u32 s67, 61
	v_lshl_add_u64 v[148:149], v[148:149], 0, s[38:39]
	s_cbranch_scc0 .LBB0_668
	s_and_b64 vcc, exec, s[36:37]
	s_cbranch_vccnz .LBB0_676
	s_and_b64 s[0:1], s[10:11], s[4:5]
	s_andn2_b64 vcc, exec, s[0:1]
	s_cbranch_vccz .LBB0_677

.LBB0_762:
	ds_read_b128 v[158:161], v153
	ds_read_b128 v[162:165], v153 offset:1024
	ds_read_b128 v[166:169], v153 offset:2048
	ds_read_b128 v[170:173], v153 offset:3072
	ds_read_b128 v[174:177], v154
	ds_read_b128 v[178:181], v154 offset:1024
	ds_read_b128 v[182:185], v154 offset:2048
	ds_read_b128 v[186:189], v154 offset:3072
	s_add_u32 s12, s65, s30
	s_addc_u32 s13, s66, 0
	s_cmp_eq_u32 s30, s50
	s_cselect_b32 s23, s11, s13
	s_cselect_b32 s22, s10, s12
	s_cselect_b32 s53, s49, s64
	s_cselect_b32 s52, s48, s1
	s_add_i32 s68, s19, 0xc000
	v_lshl_add_u64 v[144:145], v[2:3], 0, s[30:31]
	s_mov_b32 m0, s68
	s_add_i32 s67, s19, 0xe000
	ds_read_b128 v[190:193], v155
	ds_read_b128 v[194:197], v155 offset:1024
	ds_read_b128 v[198:201], v155 offset:2048
	ds_read_b128 v[202:205], v155 offset:3072
	ds_read_b128 v[206:209], v155 offset:4096
	ds_read_b128 v[210:213], v155 offset:5120
	ds_read_b128 v[214:217], v155 offset:6144
	ds_read_b128 v[218:221], v155 offset:7168
	global_load_lds_dwordx4 v[144:145], off
	s_mov_b32 m0, s67
	v_lshl_add_u64 v[144:145], v[148:149], 0, s[30:31]
	global_load_lds_dwordx4 v[144:145], off
	s_waitcnt vmcnt(8) lgkmcnt(0)
	s_barrier
	v_mfma_f32_16x16x32_bf16 v[128:131], v[158:161], v[190:193], v[128:131]
	v_mfma_f32_16x16x32_bf16 v[128:131], v[162:165], v[194:197], v[128:131]
	v_mfma_f32_16x16x32_bf16 v[116:119], v[170:173], v[194:197], v[116:119]
	v_mfma_f32_16x16x32_bf16 v[116:119], v[166:169], v[190:193], v[116:119]
	v_mfma_f32_16x16x32_bf16 v[100:103], v[166:169], v[198:201], v[100:103]
	v_mfma_f32_16x16x32_bf16 v[100:103], v[170:173], v[202:205], v[100:103]
	v_mfma_f32_16x16x32_bf16 v[112:115], v[162:165], v[202:205], v[112:115]
	v_mfma_f32_16x16x32_bf16 v[112:115], v[158:161], v[198:201], v[112:115]
	v_mfma_f32_16x16x32_bf16 v[96:99], v[158:161], v[206:209], v[96:99]
	v_mfma_f32_16x16x32_bf16 v[96:99], v[162:165], v[210:213], v[96:99]
	v_mfma_f32_16x16x32_bf16 v[84:87], v[170:173], v[210:213], v[84:87]
	v_mfma_f32_16x16x32_bf16 v[84:87], v[166:169], v[206:209], v[84:87]
	v_mfma_f32_16x16x32_bf16 v[64:67], v[166:169], v[214:217], v[64:67]
	v_mfma_f32_16x16x32_bf16 v[64:67], v[170:173], v[218:221], v[64:67]
	v_mfma_f32_16x16x32_bf16 v[80:83], v[162:165], v[218:221], v[80:83]
	v_mfma_f32_16x16x32_bf16 v[80:83], v[158:161], v[214:217], v[80:83]
	v_mfma_f32_16x16x32_bf16 v[72:75], v[174:177], v[214:217], v[72:75]
	v_mfma_f32_16x16x32_bf16 v[72:75], v[178:181], v[218:221], v[72:75]
	v_mfma_f32_16x16x32_bf16 v[68:71], v[186:189], v[218:221], v[68:71]
	v_mfma_f32_16x16x32_bf16 v[68:71], v[182:185], v[214:217], v[68:71]
	v_mfma_f32_16x16x32_bf16 v[88:91], v[182:185], v[206:209], v[88:91]
	v_mfma_f32_16x16x32_bf16 v[88:91], v[186:189], v[210:213], v[88:91]
	v_mfma_f32_16x16x32_bf16 v[92:95], v[178:181], v[210:213], v[92:95]
	v_mfma_f32_16x16x32_bf16 v[92:95], v[174:177], v[206:209], v[92:95]
	v_mfma_f32_16x16x32_bf16 v[108:111], v[174:177], v[198:201], v[108:111]
	v_mfma_f32_16x16x32_bf16 v[108:111], v[178:181], v[202:205], v[108:111]
	v_mfma_f32_16x16x32_bf16 v[104:107], v[186:189], v[202:205], v[104:107]
	v_mfma_f32_16x16x32_bf16 v[104:107], v[182:185], v[198:201], v[104:107]
	v_mfma_f32_16x16x32_bf16 v[120:123], v[182:185], v[190:193], v[120:123]
	v_mfma_f32_16x16x32_bf16 v[120:123], v[186:189], v[194:197], v[120:123]
	v_mfma_f32_16x16x32_bf16 v[124:127], v[178:181], v[194:197], v[124:127]
	v_mfma_f32_16x16x32_bf16 v[124:127], v[174:177], v[190:193], v[124:127]
	s_barrier
	s_add_i32 s12, s57, s2
	v_lshl_add_u64 v[144:145], s[52:53], 0, v[134:135]
	s_mov_b32 m0, s12
	ds_read_b128 v[190:193], v155 offset:16384
	ds_read_b128 v[194:197], v155 offset:17408
	ds_read_b128 v[198:201], v155 offset:18432
	ds_read_b128 v[202:205], v155 offset:19456
	ds_read_b128 v[206:209], v155 offset:20480
	ds_read_b128 v[210:213], v155 offset:21504
	ds_read_b128 v[214:217], v155 offset:22528
	ds_read_b128 v[218:221], v155 offset:23552
	global_load_lds_dwordx4 v[144:145], off
	s_add_i32 m0, s12, 0x2000
	s_add_u32 s12, s52, 0x4000
	v_lshl_add_u64 v[144:145], s[52:53], 0, v[138:139]
	s_addc_u32 s13, s53, 0
	s_add_i32 s14, s58, s2
	global_load_lds_dwordx4 v[144:145], off
	v_lshl_add_u64 v[144:145], s[12:13], 0, v[134:135]
	s_mov_b32 m0, s14
	v_lshl_add_u64 v[222:223], s[22:23], 0, v[136:137]
	global_load_lds_dwordx4 v[144:145], off
	s_add_i32 m0, s14, 0x2000
	v_lshl_add_u64 v[144:145], s[12:13], 0, v[138:139]
	global_load_lds_dwordx4 v[144:145], off
	s_mov_b32 m0, s19
	v_lshl_add_u64 v[144:145], s[22:23], 0, v[132:133]
	global_load_lds_dwordx4 v[144:145], off
	s_mov_b32 m0, s20
	s_nop 0
	global_load_lds_dwordx4 v[222:223], off
	s_waitcnt vmcnt(8) lgkmcnt(0)
	s_barrier
	v_mfma_f32_16x16x32_bf16 v[76:79], v[158:161], v[190:193], v[76:79]
	v_mfma_f32_16x16x32_bf16 v[76:79], v[162:165], v[194:197], v[76:79]
	v_mfma_f32_16x16x32_bf16 v[52:55], v[170:173], v[194:197], v[52:55]
	v_mfma_f32_16x16x32_bf16 v[52:55], v[166:169], v[190:193], v[52:55]
	v_mfma_f32_16x16x32_bf16 v[36:39], v[166:169], v[198:201], v[36:39]
	v_mfma_f32_16x16x32_bf16 v[36:39], v[170:173], v[202:205], v[36:39]
	v_mfma_f32_16x16x32_bf16 v[48:51], v[162:165], v[202:205], v[48:51]
	v_mfma_f32_16x16x32_bf16 v[48:51], v[158:161], v[198:201], v[48:51]
	v_mfma_f32_16x16x32_bf16 v[32:35], v[158:161], v[206:209], v[32:35]
	v_mfma_f32_16x16x32_bf16 v[32:35], v[162:165], v[210:213], v[32:35]
	v_mfma_f32_16x16x32_bf16 v[20:23], v[170:173], v[210:213], v[20:23]
	v_mfma_f32_16x16x32_bf16 v[20:23], v[166:169], v[206:209], v[20:23]
	v_mfma_f32_16x16x32_bf16 v[4:7], v[166:169], v[214:217], v[4:7]
	v_mfma_f32_16x16x32_bf16 v[4:7], v[170:173], v[218:221], v[4:7]
	v_mfma_f32_16x16x32_bf16 v[16:19], v[162:165], v[218:221], v[16:19]
	v_mfma_f32_16x16x32_bf16 v[16:19], v[158:161], v[214:217], v[16:19]
	v_mfma_f32_16x16x32_bf16 v[12:15], v[174:177], v[214:217], v[12:15]
	v_mfma_f32_16x16x32_bf16 v[12:15], v[178:181], v[218:221], v[12:15]
	v_mfma_f32_16x16x32_bf16 v[8:11], v[186:189], v[218:221], v[8:11]
	v_mfma_f32_16x16x32_bf16 v[8:11], v[182:185], v[214:217], v[8:11]
	v_mfma_f32_16x16x32_bf16 v[24:27], v[182:185], v[206:209], v[24:27]
	v_mfma_f32_16x16x32_bf16 v[24:27], v[186:189], v[210:213], v[24:27]
	v_mfma_f32_16x16x32_bf16 v[28:31], v[178:181], v[210:213], v[28:31]
	v_mfma_f32_16x16x32_bf16 v[28:31], v[174:177], v[206:209], v[28:31]
	v_mfma_f32_16x16x32_bf16 v[44:47], v[174:177], v[198:201], v[44:47]
	v_mfma_f32_16x16x32_bf16 v[44:47], v[178:181], v[202:205], v[44:47]
	v_mfma_f32_16x16x32_bf16 v[40:43], v[186:189], v[202:205], v[40:43]
	v_mfma_f32_16x16x32_bf16 v[40:43], v[182:185], v[198:201], v[40:43]
	v_mfma_f32_16x16x32_bf16 v[56:59], v[182:185], v[190:193], v[56:59]
	v_mfma_f32_16x16x32_bf16 v[56:59], v[186:189], v[194:197], v[56:59]
	v_mfma_f32_16x16x32_bf16 v[60:63], v[178:181], v[194:197], v[60:63]
	v_mfma_f32_16x16x32_bf16 v[60:63], v[174:177], v[190:193], v[60:63]
	s_barrier
	s_add_i32 s14, 0, 0x18000
	v_add_u32_e32 v1, s14, v151
	s_add_i32 s69, 0, 0x1c000
	ds_read_b128 v[158:161], v1
	ds_read_b128 v[162:165], v1 offset:1024
	ds_read_b128 v[166:169], v1 offset:2048
	ds_read_b128 v[170:173], v1 offset:3072
	v_add_u32_e32 v1, s69, v151
	ds_read_b128 v[174:177], v1
	ds_read_b128 v[178:181], v1 offset:1024
	ds_read_b128 v[182:185], v1 offset:2048
	ds_read_b128 v[186:189], v1 offset:3072
	s_add_u32 s12, s22, 0x2b0000
	s_addc_u32 s13, s23, 0
	s_mov_b32 m0, s21
	v_lshl_add_u64 v[224:225], s[12:13], 0, v[132:133]
	ds_read_b128 v[190:193], v155 offset:32768
	ds_read_b128 v[194:197], v155 offset:33792
	ds_read_b128 v[198:201], v155 offset:34816
	ds_read_b128 v[202:205], v155 offset:35840
	ds_read_b128 v[206:209], v155 offset:36864
	ds_read_b128 v[210:213], v155 offset:37888
	ds_read_b128 v[214:217], v155 offset:38912
	ds_read_b128 v[218:221], v155 offset:39936
	global_load_lds_dwordx4 v[224:225], off
	s_mov_b32 m0, s24
	v_lshl_add_u64 v[224:225], s[12:13], 0, v[136:137]
	global_load_lds_dwordx4 v[224:225], off
	s_waitcnt vmcnt(8) lgkmcnt(0)
	s_barrier
	v_mfma_f32_16x16x32_bf16 v[128:131], v[158:161], v[190:193], v[128:131]
	v_mfma_f32_16x16x32_bf16 v[128:131], v[162:165], v[194:197], v[128:131]
	v_mfma_f32_16x16x32_bf16 v[116:119], v[170:173], v[194:197], v[116:119]
	v_mfma_f32_16x16x32_bf16 v[116:119], v[166:169], v[190:193], v[116:119]
	v_mfma_f32_16x16x32_bf16 v[100:103], v[166:169], v[198:201], v[100:103]
	v_mfma_f32_16x16x32_bf16 v[100:103], v[170:173], v[202:205], v[100:103]
	v_mfma_f32_16x16x32_bf16 v[112:115], v[162:165], v[202:205], v[112:115]
	v_mfma_f32_16x16x32_bf16 v[112:115], v[158:161], v[198:201], v[112:115]
	v_mfma_f32_16x16x32_bf16 v[96:99], v[158:161], v[206:209], v[96:99]
	v_mfma_f32_16x16x32_bf16 v[96:99], v[162:165], v[210:213], v[96:99]
	v_mfma_f32_16x16x32_bf16 v[84:87], v[170:173], v[210:213], v[84:87]
	v_mfma_f32_16x16x32_bf16 v[84:87], v[166:169], v[206:209], v[84:87]
	v_mfma_f32_16x16x32_bf16 v[64:67], v[166:169], v[214:217], v[64:67]
	v_mfma_f32_16x16x32_bf16 v[64:67], v[170:173], v[218:221], v[64:67]
	v_mfma_f32_16x16x32_bf16 v[80:83], v[162:165], v[218:221], v[80:83]
	v_mfma_f32_16x16x32_bf16 v[80:83], v[158:161], v[214:217], v[80:83]
	v_mfma_f32_16x16x32_bf16 v[72:75], v[174:177], v[214:217], v[72:75]
	v_mfma_f32_16x16x32_bf16 v[72:75], v[178:181], v[218:221], v[72:75]
	v_mfma_f32_16x16x32_bf16 v[68:71], v[186:189], v[218:221], v[68:71]
	v_mfma_f32_16x16x32_bf16 v[68:71], v[182:185], v[214:217], v[68:71]
	v_mfma_f32_16x16x32_bf16 v[88:91], v[182:185], v[206:209], v[88:91]
	v_mfma_f32_16x16x32_bf16 v[88:91], v[186:189], v[210:213], v[88:91]
	v_mfma_f32_16x16x32_bf16 v[92:95], v[178:181], v[210:213], v[92:95]
	v_mfma_f32_16x16x32_bf16 v[92:95], v[174:177], v[206:209], v[92:95]
	v_mfma_f32_16x16x32_bf16 v[108:111], v[174:177], v[198:201], v[108:111]
	v_mfma_f32_16x16x32_bf16 v[108:111], v[178:181], v[202:205], v[108:111]
	v_mfma_f32_16x16x32_bf16 v[104:107], v[186:189], v[202:205], v[104:107]
	v_mfma_f32_16x16x32_bf16 v[104:107], v[182:185], v[198:201], v[104:107]
	v_mfma_f32_16x16x32_bf16 v[120:123], v[182:185], v[190:193], v[120:123]
	v_mfma_f32_16x16x32_bf16 v[120:123], v[186:189], v[194:197], v[120:123]
	v_mfma_f32_16x16x32_bf16 v[124:127], v[178:181], v[194:197], v[124:127]
	v_mfma_f32_16x16x32_bf16 v[124:127], v[174:177], v[190:193], v[124:127]
	s_barrier
	s_add_u32 s12, s52, 0x8000
	s_addc_u32 s13, s53, 0
	s_add_i32 s14, s14, s2
	v_lshl_add_u64 v[224:225], s[12:13], 0, v[134:135]
	s_mov_b32 m0, s14
	ds_read_b128 v[190:193], v155 offset:49152
	ds_read_b128 v[194:197], v155 offset:50176
	ds_read_b128 v[198:201], v155 offset:51200
	ds_read_b128 v[202:205], v155 offset:52224
	ds_read_b128 v[206:209], v155 offset:53248
	ds_read_b128 v[210:213], v155 offset:54272
	ds_read_b128 v[214:217], v155 offset:55296
	ds_read_b128 v[218:221], v155 offset:56320
	global_load_lds_dwordx4 v[224:225], off
	s_add_i32 m0, s14, 0x2000
	v_lshl_add_u64 v[224:225], s[12:13], 0, v[138:139]
	s_add_u32 s12, s52, 0xc000
	s_addc_u32 s13, s53, 0
	s_add_i32 s14, s69, s2
	global_load_lds_dwordx4 v[224:225], off
	v_lshl_add_u64 v[224:225], s[12:13], 0, v[134:135]
	s_mov_b32 m0, s14
	v_lshl_add_u64 v[144:145], v[144:145], 0, s[40:41]
	global_load_lds_dwordx4 v[224:225], off
	s_add_i32 m0, s14, 0x2000
	v_lshl_add_u64 v[224:225], s[12:13], 0, v[138:139]
	global_load_lds_dwordx4 v[224:225], off
	s_mov_b32 m0, s33
	s_nop 0
	global_load_lds_dwordx4 v[144:145], off
	s_mov_b32 m0, s54
	v_lshl_add_u64 v[144:145], v[222:223], 0, s[40:41]
	global_load_lds_dwordx4 v[144:145], off
	s_waitcnt vmcnt(8) lgkmcnt(0)
	s_barrier
	v_mfma_f32_16x16x32_bf16 v[76:79], v[158:161], v[190:193], v[76:79]
	v_mfma_f32_16x16x32_bf16 v[76:79], v[162:165], v[194:197], v[76:79]
	v_mfma_f32_16x16x32_bf16 v[52:55], v[170:173], v[194:197], v[52:55]
	v_mfma_f32_16x16x32_bf16 v[52:55], v[166:169], v[190:193], v[52:55]
	v_mfma_f32_16x16x32_bf16 v[36:39], v[166:169], v[198:201], v[36:39]
	v_mfma_f32_16x16x32_bf16 v[36:39], v[170:173], v[202:205], v[36:39]
	v_mfma_f32_16x16x32_bf16 v[48:51], v[162:165], v[202:205], v[48:51]
	v_mfma_f32_16x16x32_bf16 v[48:51], v[158:161], v[198:201], v[48:51]
	v_mfma_f32_16x16x32_bf16 v[32:35], v[158:161], v[206:209], v[32:35]
	v_mfma_f32_16x16x32_bf16 v[32:35], v[162:165], v[210:213], v[32:35]
	v_mfma_f32_16x16x32_bf16 v[20:23], v[170:173], v[210:213], v[20:23]
	v_mfma_f32_16x16x32_bf16 v[20:23], v[166:169], v[206:209], v[20:23]
	v_mfma_f32_16x16x32_bf16 v[4:7], v[166:169], v[214:217], v[4:7]
	v_mfma_f32_16x16x32_bf16 v[4:7], v[170:173], v[218:221], v[4:7]
	v_mfma_f32_16x16x32_bf16 v[16:19], v[162:165], v[218:221], v[16:19]
	v_mfma_f32_16x16x32_bf16 v[16:19], v[158:161], v[214:217], v[16:19]
	v_mfma_f32_16x16x32_bf16 v[12:15], v[174:177], v[214:217], v[12:15]
	v_mfma_f32_16x16x32_bf16 v[12:15], v[178:181], v[218:221], v[12:15]
	v_mfma_f32_16x16x32_bf16 v[8:11], v[186:189], v[218:221], v[8:11]
	v_mfma_f32_16x16x32_bf16 v[8:11], v[182:185], v[214:217], v[8:11]
	v_mfma_f32_16x16x32_bf16 v[24:27], v[182:185], v[206:209], v[24:27]
	v_mfma_f32_16x16x32_bf16 v[24:27], v[186:189], v[210:213], v[24:27]
	v_mfma_f32_16x16x32_bf16 v[28:31], v[178:181], v[210:213], v[28:31]
	v_mfma_f32_16x16x32_bf16 v[28:31], v[174:177], v[206:209], v[28:31]
	v_mfma_f32_16x16x32_bf16 v[44:47], v[174:177], v[198:201], v[44:47]
	v_mfma_f32_16x16x32_bf16 v[44:47], v[178:181], v[202:205], v[44:47]
	v_mfma_f32_16x16x32_bf16 v[40:43], v[186:189], v[202:205], v[40:43]
	v_mfma_f32_16x16x32_bf16 v[40:43], v[182:185], v[198:201], v[40:43]
	v_mfma_f32_16x16x32_bf16 v[56:59], v[182:185], v[190:193], v[56:59]
	v_mfma_f32_16x16x32_bf16 v[56:59], v[186:189], v[194:197], v[56:59]
	v_mfma_f32_16x16x32_bf16 v[60:63], v[178:181], v[194:197], v[60:63]
	v_mfma_f32_16x16x32_bf16 v[60:63], v[174:177], v[190:193], v[60:63]
	s_barrier
	s_add_i32 s0, s0, 2
	s_add_u32 s1, s1, 0x10000
	s_addc_u32 s64, s64, 0
	s_add_u32 s65, s65, 0x100
	s_addc_u32 s66, s66, 0
	s_add_u32 s50, s50, 0xffffff00
	s_addc_u32 s51, s51, -1
	v_lshl_add_u64 v[2:3], v[2:3], 0, s[44:45]
	s_cmpk_gt_u32 s0, 0xa9
	v_lshl_add_u64 v[148:149], v[148:149], 0, s[44:45]
	s_cbranch_scc0 .LBB0_762
	s_and_b64 vcc, exec, s[42:43]
	s_cbranch_vccz .LBB0_765
	s_barrier

.LBB0_801:
	ds_read_b128 v[158:161], v155
	ds_read_b128 v[162:165], v155 offset:1024
	ds_read_b128 v[166:169], v155 offset:2048
	ds_read_b128 v[170:173], v155 offset:3072
	ds_read_b128 v[174:177], v156
	ds_read_b128 v[178:181], v156 offset:1024
	ds_read_b128 v[182:185], v156 offset:2048
	ds_read_b128 v[186:189], v156 offset:3072
	s_add_u32 s12, s72, s36
	s_addc_u32 s13, s73, 0
	s_cmp_eq_u32 s36, s8
	s_cselect_b32 s23, s0, s13
	s_cselect_b32 s22, s1, s12
	s_cselect_b32 s57, s45, s71
	s_cselect_b32 s56, s68, s70
	s_add_i32 s75, s33, 0xc000
	v_lshl_add_u64 v[144:145], v[2:3], 0, s[36:37]
	s_mov_b32 m0, s75
	s_add_i32 s74, s33, 0xe000
	ds_read_b128 v[190:193], v157
	ds_read_b128 v[194:197], v157 offset:1024
	ds_read_b128 v[198:201], v157 offset:2048
	ds_read_b128 v[202:205], v157 offset:3072
	ds_read_b128 v[206:209], v157 offset:4096
	ds_read_b128 v[210:213], v157 offset:5120
	ds_read_b128 v[214:217], v157 offset:6144
	ds_read_b128 v[218:221], v157 offset:7168
	global_load_lds_dwordx4 v[144:145], off
	s_mov_b32 m0, s74
	v_lshl_add_u64 v[144:145], v[148:149], 0, s[36:37]
	global_load_lds_dwordx4 v[144:145], off
	s_waitcnt vmcnt(8) lgkmcnt(0)
	s_barrier
	v_mfma_f32_16x16x32_bf16 v[120:123], v[158:161], v[190:193], v[120:123]
	v_mfma_f32_16x16x32_bf16 v[120:123], v[162:165], v[194:197], v[120:123]
	v_mfma_f32_16x16x32_bf16 v[116:119], v[170:173], v[194:197], v[116:119]
	v_mfma_f32_16x16x32_bf16 v[116:119], v[166:169], v[190:193], v[116:119]
	v_mfma_f32_16x16x32_bf16 v[100:103], v[166:169], v[198:201], v[100:103]
	v_mfma_f32_16x16x32_bf16 v[100:103], v[170:173], v[202:205], v[100:103]
	v_mfma_f32_16x16x32_bf16 v[104:107], v[162:165], v[202:205], v[104:107]
	v_mfma_f32_16x16x32_bf16 v[104:107], v[158:161], v[198:201], v[104:107]
	v_mfma_f32_16x16x32_bf16 v[88:91], v[158:161], v[206:209], v[88:91]
	v_mfma_f32_16x16x32_bf16 v[88:91], v[162:165], v[210:213], v[88:91]
	v_mfma_f32_16x16x32_bf16 v[84:87], v[170:173], v[210:213], v[84:87]
	v_mfma_f32_16x16x32_bf16 v[84:87], v[166:169], v[206:209], v[84:87]
	v_mfma_f32_16x16x32_bf16 v[68:71], v[166:169], v[214:217], v[68:71]
	v_mfma_f32_16x16x32_bf16 v[68:71], v[170:173], v[218:221], v[68:71]
	v_mfma_f32_16x16x32_bf16 v[72:75], v[162:165], v[218:221], v[72:75]
	v_mfma_f32_16x16x32_bf16 v[72:75], v[158:161], v[214:217], v[72:75]
	v_mfma_f32_16x16x32_bf16 v[80:83], v[174:177], v[214:217], v[80:83]
	v_mfma_f32_16x16x32_bf16 v[80:83], v[178:181], v[218:221], v[80:83]
	v_mfma_f32_16x16x32_bf16 v[76:79], v[186:189], v[218:221], v[76:79]
	v_mfma_f32_16x16x32_bf16 v[76:79], v[182:185], v[214:217], v[76:79]
	v_mfma_f32_16x16x32_bf16 v[92:95], v[182:185], v[206:209], v[92:95]
	v_mfma_f32_16x16x32_bf16 v[92:95], v[186:189], v[210:213], v[92:95]
	v_mfma_f32_16x16x32_bf16 v[96:99], v[178:181], v[210:213], v[96:99]
	v_mfma_f32_16x16x32_bf16 v[96:99], v[174:177], v[206:209], v[96:99]
	v_mfma_f32_16x16x32_bf16 v[112:115], v[174:177], v[198:201], v[112:115]
	v_mfma_f32_16x16x32_bf16 v[112:115], v[178:181], v[202:205], v[112:115]
	v_mfma_f32_16x16x32_bf16 v[108:111], v[186:189], v[202:205], v[108:111]
	v_mfma_f32_16x16x32_bf16 v[108:111], v[182:185], v[198:201], v[108:111]
	v_mfma_f32_16x16x32_bf16 v[124:127], v[182:185], v[190:193], v[124:127]
	v_mfma_f32_16x16x32_bf16 v[124:127], v[186:189], v[194:197], v[124:127]
	v_mfma_f32_16x16x32_bf16 v[128:131], v[178:181], v[194:197], v[128:131]
	v_mfma_f32_16x16x32_bf16 v[128:131], v[174:177], v[190:193], v[128:131]
	s_barrier
	s_add_i32 s12, s60, s2
	v_lshl_add_u64 v[144:145], s[56:57], 0, v[134:135]
	s_mov_b32 m0, s12
	ds_read_b128 v[190:193], v157 offset:16384
	ds_read_b128 v[194:197], v157 offset:17408
	ds_read_b128 v[198:201], v157 offset:18432
	ds_read_b128 v[202:205], v157 offset:19456
	ds_read_b128 v[206:209], v157 offset:20480
	ds_read_b128 v[210:213], v157 offset:21504
	ds_read_b128 v[214:217], v157 offset:22528
	ds_read_b128 v[218:221], v157 offset:23552
	global_load_lds_dwordx4 v[144:145], off
	s_add_i32 m0, s12, 0x2000
	s_add_u32 s12, s56, 0x4000
	v_lshl_add_u64 v[144:145], s[56:57], 0, v[138:139]
	s_addc_u32 s13, s57, 0
	s_add_i32 s14, s61, s2
	global_load_lds_dwordx4 v[144:145], off
	v_lshl_add_u64 v[144:145], s[12:13], 0, v[134:135]
	s_mov_b32 m0, s14
	v_lshl_add_u64 v[222:223], s[22:23], 0, v[136:137]
	global_load_lds_dwordx4 v[144:145], off
	s_add_i32 m0, s14, 0x2000
	v_lshl_add_u64 v[144:145], s[12:13], 0, v[138:139]
	global_load_lds_dwordx4 v[144:145], off
	s_mov_b32 m0, s33
	v_lshl_add_u64 v[144:145], s[22:23], 0, v[132:133]
	global_load_lds_dwordx4 v[144:145], off
	s_mov_b32 m0, s53
	s_nop 0
	global_load_lds_dwordx4 v[222:223], off
	s_waitcnt vmcnt(8) lgkmcnt(0)
	s_barrier
	v_mfma_f32_16x16x32_bf16 v[56:59], v[158:161], v[190:193], v[56:59]
	v_mfma_f32_16x16x32_bf16 v[56:59], v[162:165], v[194:197], v[56:59]
	v_mfma_f32_16x16x32_bf16 v[52:55], v[170:173], v[194:197], v[52:55]
	v_mfma_f32_16x16x32_bf16 v[52:55], v[166:169], v[190:193], v[52:55]
	v_mfma_f32_16x16x32_bf16 v[36:39], v[166:169], v[198:201], v[36:39]
	v_mfma_f32_16x16x32_bf16 v[36:39], v[170:173], v[202:205], v[36:39]
	v_mfma_f32_16x16x32_bf16 v[40:43], v[162:165], v[202:205], v[40:43]
	v_mfma_f32_16x16x32_bf16 v[40:43], v[158:161], v[198:201], v[40:43]
	v_mfma_f32_16x16x32_bf16 v[24:27], v[158:161], v[206:209], v[24:27]
	v_mfma_f32_16x16x32_bf16 v[24:27], v[162:165], v[210:213], v[24:27]
	v_mfma_f32_16x16x32_bf16 v[20:23], v[170:173], v[210:213], v[20:23]
	v_mfma_f32_16x16x32_bf16 v[20:23], v[166:169], v[206:209], v[20:23]
	v_mfma_f32_16x16x32_bf16 v[4:7], v[166:169], v[214:217], v[4:7]
	v_mfma_f32_16x16x32_bf16 v[4:7], v[170:173], v[218:221], v[4:7]
	v_mfma_f32_16x16x32_bf16 v[8:11], v[162:165], v[218:221], v[8:11]
	v_mfma_f32_16x16x32_bf16 v[8:11], v[158:161], v[214:217], v[8:11]
	v_mfma_f32_16x16x32_bf16 v[16:19], v[174:177], v[214:217], v[16:19]
	v_mfma_f32_16x16x32_bf16 v[16:19], v[178:181], v[218:221], v[16:19]
	v_mfma_f32_16x16x32_bf16 v[12:15], v[186:189], v[218:221], v[12:15]
	v_mfma_f32_16x16x32_bf16 v[12:15], v[182:185], v[214:217], v[12:15]
	v_mfma_f32_16x16x32_bf16 v[28:31], v[182:185], v[206:209], v[28:31]
	v_mfma_f32_16x16x32_bf16 v[28:31], v[186:189], v[210:213], v[28:31]
	v_mfma_f32_16x16x32_bf16 v[32:35], v[178:181], v[210:213], v[32:35]
	v_mfma_f32_16x16x32_bf16 v[32:35], v[174:177], v[206:209], v[32:35]
	v_mfma_f32_16x16x32_bf16 v[48:51], v[174:177], v[198:201], v[48:51]
	v_mfma_f32_16x16x32_bf16 v[48:51], v[178:181], v[202:205], v[48:51]
	v_mfma_f32_16x16x32_bf16 v[44:47], v[186:189], v[202:205], v[44:47]
	v_mfma_f32_16x16x32_bf16 v[44:47], v[182:185], v[198:201], v[44:47]
	v_mfma_f32_16x16x32_bf16 v[60:63], v[182:185], v[190:193], v[60:63]
	v_mfma_f32_16x16x32_bf16 v[60:63], v[186:189], v[194:197], v[60:63]
	v_mfma_f32_16x16x32_bf16 v[64:67], v[178:181], v[194:197], v[64:67]
	v_mfma_f32_16x16x32_bf16 v[64:67], v[174:177], v[190:193], v[64:67]
	s_barrier
	s_add_i32 s14, 0, 0x18000
	v_add_u32_e32 v1, s14, v152
	s_add_i32 s76, 0, 0x1c000
	ds_read_b128 v[158:161], v1
	ds_read_b128 v[162:165], v1 offset:1024
	ds_read_b128 v[166:169], v1 offset:2048
	ds_read_b128 v[170:173], v1 offset:3072
	v_add_u32_e32 v1, s76, v152
	ds_read_b128 v[174:177], v1
	ds_read_b128 v[178:181], v1 offset:1024
	ds_read_b128 v[182:185], v1 offset:2048
	ds_read_b128 v[186:189], v1 offset:3072
	s_add_u32 s12, s22, 0x100000
	s_addc_u32 s13, s23, 0
	s_mov_b32 m0, s55
	v_lshl_add_u64 v[224:225], s[12:13], 0, v[132:133]
	ds_read_b128 v[190:193], v157 offset:32768
	ds_read_b128 v[194:197], v157 offset:33792
	ds_read_b128 v[198:201], v157 offset:34816
	ds_read_b128 v[202:205], v157 offset:35840
	ds_read_b128 v[206:209], v157 offset:36864
	ds_read_b128 v[210:213], v157 offset:37888
	ds_read_b128 v[214:217], v157 offset:38912
	ds_read_b128 v[218:221], v157 offset:39936
	global_load_lds_dwordx4 v[224:225], off
	s_mov_b32 m0, s58
	v_lshl_add_u64 v[224:225], s[12:13], 0, v[136:137]
	global_load_lds_dwordx4 v[224:225], off
	s_waitcnt vmcnt(8) lgkmcnt(0)
	s_barrier
	v_mfma_f32_16x16x32_bf16 v[120:123], v[158:161], v[190:193], v[120:123]
	v_mfma_f32_16x16x32_bf16 v[120:123], v[162:165], v[194:197], v[120:123]
	v_mfma_f32_16x16x32_bf16 v[116:119], v[170:173], v[194:197], v[116:119]
	v_mfma_f32_16x16x32_bf16 v[116:119], v[166:169], v[190:193], v[116:119]
	v_mfma_f32_16x16x32_bf16 v[100:103], v[166:169], v[198:201], v[100:103]
	v_mfma_f32_16x16x32_bf16 v[100:103], v[170:173], v[202:205], v[100:103]
	v_mfma_f32_16x16x32_bf16 v[104:107], v[162:165], v[202:205], v[104:107]
	v_mfma_f32_16x16x32_bf16 v[104:107], v[158:161], v[198:201], v[104:107]
	v_mfma_f32_16x16x32_bf16 v[88:91], v[158:161], v[206:209], v[88:91]
	v_mfma_f32_16x16x32_bf16 v[88:91], v[162:165], v[210:213], v[88:91]
	v_mfma_f32_16x16x32_bf16 v[84:87], v[170:173], v[210:213], v[84:87]
	v_mfma_f32_16x16x32_bf16 v[84:87], v[166:169], v[206:209], v[84:87]
	v_mfma_f32_16x16x32_bf16 v[68:71], v[166:169], v[214:217], v[68:71]
	v_mfma_f32_16x16x32_bf16 v[68:71], v[170:173], v[218:221], v[68:71]
	v_mfma_f32_16x16x32_bf16 v[72:75], v[162:165], v[218:221], v[72:75]
	v_mfma_f32_16x16x32_bf16 v[72:75], v[158:161], v[214:217], v[72:75]
	v_mfma_f32_16x16x32_bf16 v[80:83], v[174:177], v[214:217], v[80:83]
	v_mfma_f32_16x16x32_bf16 v[80:83], v[178:181], v[218:221], v[80:83]
	v_mfma_f32_16x16x32_bf16 v[76:79], v[186:189], v[218:221], v[76:79]
	v_mfma_f32_16x16x32_bf16 v[76:79], v[182:185], v[214:217], v[76:79]
	v_mfma_f32_16x16x32_bf16 v[92:95], v[182:185], v[206:209], v[92:95]
	v_mfma_f32_16x16x32_bf16 v[92:95], v[186:189], v[210:213], v[92:95]
	v_mfma_f32_16x16x32_bf16 v[96:99], v[178:181], v[210:213], v[96:99]
	v_mfma_f32_16x16x32_bf16 v[96:99], v[174:177], v[206:209], v[96:99]
	v_mfma_f32_16x16x32_bf16 v[112:115], v[174:177], v[198:201], v[112:115]
	v_mfma_f32_16x16x32_bf16 v[112:115], v[178:181], v[202:205], v[112:115]
	v_mfma_f32_16x16x32_bf16 v[108:111], v[186:189], v[202:205], v[108:111]
	v_mfma_f32_16x16x32_bf16 v[108:111], v[182:185], v[198:201], v[108:111]
	v_mfma_f32_16x16x32_bf16 v[124:127], v[182:185], v[190:193], v[124:127]
	v_mfma_f32_16x16x32_bf16 v[124:127], v[186:189], v[194:197], v[124:127]
	v_mfma_f32_16x16x32_bf16 v[128:131], v[178:181], v[194:197], v[128:131]
	v_mfma_f32_16x16x32_bf16 v[128:131], v[174:177], v[190:193], v[128:131]
	s_barrier
	s_add_u32 s12, s56, 0x8000
	s_addc_u32 s13, s57, 0
	s_add_i32 s14, s14, s2
	v_lshl_add_u64 v[224:225], s[12:13], 0, v[134:135]
	s_mov_b32 m0, s14
	ds_read_b128 v[190:193], v157 offset:49152
	ds_read_b128 v[194:197], v157 offset:50176
	ds_read_b128 v[198:201], v157 offset:51200
	ds_read_b128 v[202:205], v157 offset:52224
	ds_read_b128 v[206:209], v157 offset:53248
	ds_read_b128 v[210:213], v157 offset:54272
	ds_read_b128 v[214:217], v157 offset:55296
	ds_read_b128 v[218:221], v157 offset:56320
	global_load_lds_dwordx4 v[224:225], off
	s_add_i32 m0, s14, 0x2000
	v_lshl_add_u64 v[224:225], s[12:13], 0, v[138:139]
	s_add_u32 s12, s56, 0xc000
	s_addc_u32 s13, s57, 0
	s_add_i32 s14, s76, s2
	global_load_lds_dwordx4 v[224:225], off
	v_lshl_add_u64 v[224:225], s[12:13], 0, v[134:135]
	s_mov_b32 m0, s14
	v_lshl_add_u64 v[144:145], v[144:145], 0, s[34:35]
	global_load_lds_dwordx4 v[224:225], off
	s_add_i32 m0, s14, 0x2000
	v_lshl_add_u64 v[224:225], s[12:13], 0, v[138:139]
	global_load_lds_dwordx4 v[224:225], off
	s_mov_b32 m0, s16
	s_nop 0
	global_load_lds_dwordx4 v[144:145], off
	s_mov_b32 m0, s59
	v_lshl_add_u64 v[144:145], v[222:223], 0, s[34:35]
	global_load_lds_dwordx4 v[144:145], off
	s_waitcnt vmcnt(8) lgkmcnt(0)
	s_barrier
	v_mfma_f32_16x16x32_bf16 v[56:59], v[158:161], v[190:193], v[56:59]
	v_mfma_f32_16x16x32_bf16 v[56:59], v[162:165], v[194:197], v[56:59]
	v_mfma_f32_16x16x32_bf16 v[52:55], v[170:173], v[194:197], v[52:55]
	v_mfma_f32_16x16x32_bf16 v[52:55], v[166:169], v[190:193], v[52:55]
	v_mfma_f32_16x16x32_bf16 v[36:39], v[166:169], v[198:201], v[36:39]
	v_mfma_f32_16x16x32_bf16 v[36:39], v[170:173], v[202:205], v[36:39]
	v_mfma_f32_16x16x32_bf16 v[40:43], v[162:165], v[202:205], v[40:43]
	v_mfma_f32_16x16x32_bf16 v[40:43], v[158:161], v[198:201], v[40:43]
	v_mfma_f32_16x16x32_bf16 v[24:27], v[158:161], v[206:209], v[24:27]
	v_mfma_f32_16x16x32_bf16 v[24:27], v[162:165], v[210:213], v[24:27]
	v_mfma_f32_16x16x32_bf16 v[20:23], v[170:173], v[210:213], v[20:23]
	v_mfma_f32_16x16x32_bf16 v[20:23], v[166:169], v[206:209], v[20:23]
	v_mfma_f32_16x16x32_bf16 v[4:7], v[166:169], v[214:217], v[4:7]
	v_mfma_f32_16x16x32_bf16 v[4:7], v[170:173], v[218:221], v[4:7]
	v_mfma_f32_16x16x32_bf16 v[8:11], v[162:165], v[218:221], v[8:11]
	v_mfma_f32_16x16x32_bf16 v[8:11], v[158:161], v[214:217], v[8:11]
	v_mfma_f32_16x16x32_bf16 v[16:19], v[174:177], v[214:217], v[16:19]
	v_mfma_f32_16x16x32_bf16 v[16:19], v[178:181], v[218:221], v[16:19]
	v_mfma_f32_16x16x32_bf16 v[12:15], v[186:189], v[218:221], v[12:15]
	v_mfma_f32_16x16x32_bf16 v[12:15], v[182:185], v[214:217], v[12:15]
	v_mfma_f32_16x16x32_bf16 v[28:31], v[182:185], v[206:209], v[28:31]
	v_mfma_f32_16x16x32_bf16 v[28:31], v[186:189], v[210:213], v[28:31]
	v_mfma_f32_16x16x32_bf16 v[32:35], v[178:181], v[210:213], v[32:35]
	v_mfma_f32_16x16x32_bf16 v[32:35], v[174:177], v[206:209], v[32:35]
	v_mfma_f32_16x16x32_bf16 v[48:51], v[174:177], v[198:201], v[48:51]
	v_mfma_f32_16x16x32_bf16 v[48:51], v[178:181], v[202:205], v[48:51]
	v_mfma_f32_16x16x32_bf16 v[44:47], v[186:189], v[202:205], v[44:47]
	v_mfma_f32_16x16x32_bf16 v[44:47], v[182:185], v[198:201], v[44:47]
	v_mfma_f32_16x16x32_bf16 v[60:63], v[182:185], v[190:193], v[60:63]
	v_mfma_f32_16x16x32_bf16 v[60:63], v[186:189], v[194:197], v[60:63]
	v_mfma_f32_16x16x32_bf16 v[64:67], v[178:181], v[194:197], v[64:67]
	v_mfma_f32_16x16x32_bf16 v[64:67], v[174:177], v[190:193], v[64:67]
	s_barrier
	s_add_i32 s69, s69, 2
	s_add_u32 s70, s70, 0x10000
	s_addc_u32 s71, s71, 0
	s_add_u32 s72, s72, 0x100
	s_addc_u32 s73, s73, 0
	s_add_u32 s8, s8, 0xffffff00
	s_addc_u32 s9, s9, -1
	v_lshl_add_u64 v[2:3], v[2:3], 0, s[40:41]
	s_cmp_gt_u32 s69, 61
	v_lshl_add_u64 v[148:149], v[148:149], 0, s[40:41]
	s_cbranch_scc0 .LBB0_801
	s_and_b64 vcc, exec, s[38:39]
	s_cbranch_vccnz .LBB0_809
	s_and_b64 s[0:1], s[10:11], s[6:7]
	s_andn2_b64 vcc, exec, s[0:1]
	s_cbranch_vccz .LBB0_810

.LBB0_896:
	ds_read_b128 v[158:161], v153
	ds_read_b128 v[162:165], v153 offset:1024
	ds_read_b128 v[166:169], v153 offset:2048
	ds_read_b128 v[170:173], v153 offset:3072
	ds_read_b128 v[174:177], v154
	ds_read_b128 v[178:181], v154 offset:1024
	ds_read_b128 v[182:185], v154 offset:2048
	ds_read_b128 v[186:189], v154 offset:3072
	s_add_u32 s12, s60, s26
	s_addc_u32 s13, s61, 0
	s_cmp_eq_u32 s26, s46
	s_cselect_b32 s23, s9, s13
	s_cselect_b32 s22, s8, s12
	s_cselect_b32 s49, s45, s59
	s_cselect_b32 s48, s44, s1
	s_add_i32 s63, s18, 0xc000
	v_lshl_add_u64 v[144:145], v[2:3], 0, s[26:27]
	s_mov_b32 m0, s63
	s_add_i32 s62, s18, 0xe000
	ds_read_b128 v[190:193], v155
	ds_read_b128 v[194:197], v155 offset:1024
	ds_read_b128 v[198:201], v155 offset:2048
	ds_read_b128 v[202:205], v155 offset:3072
	ds_read_b128 v[206:209], v155 offset:4096
	ds_read_b128 v[210:213], v155 offset:5120
	ds_read_b128 v[214:217], v155 offset:6144
	ds_read_b128 v[218:221], v155 offset:7168
	global_load_lds_dwordx4 v[144:145], off
	s_mov_b32 m0, s62
	v_lshl_add_u64 v[144:145], v[148:149], 0, s[26:27]
	global_load_lds_dwordx4 v[144:145], off
	s_waitcnt vmcnt(8) lgkmcnt(0)
	s_barrier
	v_mfma_f32_16x16x32_bf16 v[128:131], v[158:161], v[190:193], v[128:131]
	v_mfma_f32_16x16x32_bf16 v[128:131], v[162:165], v[194:197], v[128:131]
	v_mfma_f32_16x16x32_bf16 v[116:119], v[170:173], v[194:197], v[116:119]
	v_mfma_f32_16x16x32_bf16 v[116:119], v[166:169], v[190:193], v[116:119]
	v_mfma_f32_16x16x32_bf16 v[100:103], v[166:169], v[198:201], v[100:103]
	v_mfma_f32_16x16x32_bf16 v[100:103], v[170:173], v[202:205], v[100:103]
	v_mfma_f32_16x16x32_bf16 v[112:115], v[162:165], v[202:205], v[112:115]
	v_mfma_f32_16x16x32_bf16 v[112:115], v[158:161], v[198:201], v[112:115]
	v_mfma_f32_16x16x32_bf16 v[96:99], v[158:161], v[206:209], v[96:99]
	v_mfma_f32_16x16x32_bf16 v[96:99], v[162:165], v[210:213], v[96:99]
	v_mfma_f32_16x16x32_bf16 v[84:87], v[170:173], v[210:213], v[84:87]
	v_mfma_f32_16x16x32_bf16 v[84:87], v[166:169], v[206:209], v[84:87]
	v_mfma_f32_16x16x32_bf16 v[64:67], v[166:169], v[214:217], v[64:67]
	v_mfma_f32_16x16x32_bf16 v[64:67], v[170:173], v[218:221], v[64:67]
	v_mfma_f32_16x16x32_bf16 v[80:83], v[162:165], v[218:221], v[80:83]
	v_mfma_f32_16x16x32_bf16 v[80:83], v[158:161], v[214:217], v[80:83]
	v_mfma_f32_16x16x32_bf16 v[72:75], v[174:177], v[214:217], v[72:75]
	v_mfma_f32_16x16x32_bf16 v[72:75], v[178:181], v[218:221], v[72:75]
	v_mfma_f32_16x16x32_bf16 v[68:71], v[186:189], v[218:221], v[68:71]
	v_mfma_f32_16x16x32_bf16 v[68:71], v[182:185], v[214:217], v[68:71]
	v_mfma_f32_16x16x32_bf16 v[88:91], v[182:185], v[206:209], v[88:91]
	v_mfma_f32_16x16x32_bf16 v[88:91], v[186:189], v[210:213], v[88:91]
	v_mfma_f32_16x16x32_bf16 v[92:95], v[178:181], v[210:213], v[92:95]
	v_mfma_f32_16x16x32_bf16 v[92:95], v[174:177], v[206:209], v[92:95]
	v_mfma_f32_16x16x32_bf16 v[108:111], v[174:177], v[198:201], v[108:111]
	v_mfma_f32_16x16x32_bf16 v[108:111], v[178:181], v[202:205], v[108:111]
	v_mfma_f32_16x16x32_bf16 v[104:107], v[186:189], v[202:205], v[104:107]
	v_mfma_f32_16x16x32_bf16 v[104:107], v[182:185], v[198:201], v[104:107]
	v_mfma_f32_16x16x32_bf16 v[120:123], v[182:185], v[190:193], v[120:123]
	v_mfma_f32_16x16x32_bf16 v[120:123], v[186:189], v[194:197], v[120:123]
	v_mfma_f32_16x16x32_bf16 v[124:127], v[178:181], v[194:197], v[124:127]
	v_mfma_f32_16x16x32_bf16 v[124:127], v[174:177], v[190:193], v[124:127]
	s_barrier
	s_add_i32 s12, s52, s17
	v_lshl_add_u64 v[144:145], s[48:49], 0, v[134:135]
	s_mov_b32 m0, s12
	ds_read_b128 v[190:193], v155 offset:16384
	ds_read_b128 v[194:197], v155 offset:17408
	ds_read_b128 v[198:201], v155 offset:18432
	ds_read_b128 v[202:205], v155 offset:19456
	ds_read_b128 v[206:209], v155 offset:20480
	ds_read_b128 v[210:213], v155 offset:21504
	ds_read_b128 v[214:217], v155 offset:22528
	ds_read_b128 v[218:221], v155 offset:23552
	global_load_lds_dwordx4 v[144:145], off
	s_add_i32 m0, s12, 0x2000
	s_add_u32 s12, s48, 0x4000
	v_lshl_add_u64 v[144:145], s[48:49], 0, v[138:139]
	s_addc_u32 s13, s49, 0
	s_add_i32 s14, s53, s17
	global_load_lds_dwordx4 v[144:145], off
	v_lshl_add_u64 v[144:145], s[12:13], 0, v[134:135]
	s_mov_b32 m0, s14
	v_lshl_add_u64 v[222:223], s[22:23], 0, v[136:137]
	global_load_lds_dwordx4 v[144:145], off
	s_add_i32 m0, s14, 0x2000
	v_lshl_add_u64 v[144:145], s[12:13], 0, v[138:139]
	global_load_lds_dwordx4 v[144:145], off
	s_mov_b32 m0, s18
	v_lshl_add_u64 v[144:145], s[22:23], 0, v[132:133]
	global_load_lds_dwordx4 v[144:145], off
	s_mov_b32 m0, s19
	s_nop 0
	global_load_lds_dwordx4 v[222:223], off
	s_waitcnt vmcnt(8) lgkmcnt(0)
	s_barrier
	v_mfma_f32_16x16x32_bf16 v[76:79], v[158:161], v[190:193], v[76:79]
	v_mfma_f32_16x16x32_bf16 v[76:79], v[162:165], v[194:197], v[76:79]
	v_mfma_f32_16x16x32_bf16 v[52:55], v[170:173], v[194:197], v[52:55]
	v_mfma_f32_16x16x32_bf16 v[52:55], v[166:169], v[190:193], v[52:55]
	v_mfma_f32_16x16x32_bf16 v[36:39], v[166:169], v[198:201], v[36:39]
	v_mfma_f32_16x16x32_bf16 v[36:39], v[170:173], v[202:205], v[36:39]
	v_mfma_f32_16x16x32_bf16 v[48:51], v[162:165], v[202:205], v[48:51]
	v_mfma_f32_16x16x32_bf16 v[48:51], v[158:161], v[198:201], v[48:51]
	v_mfma_f32_16x16x32_bf16 v[32:35], v[158:161], v[206:209], v[32:35]
	v_mfma_f32_16x16x32_bf16 v[32:35], v[162:165], v[210:213], v[32:35]
	v_mfma_f32_16x16x32_bf16 v[20:23], v[170:173], v[210:213], v[20:23]
	v_mfma_f32_16x16x32_bf16 v[20:23], v[166:169], v[206:209], v[20:23]
	v_mfma_f32_16x16x32_bf16 v[4:7], v[166:169], v[214:217], v[4:7]
	v_mfma_f32_16x16x32_bf16 v[4:7], v[170:173], v[218:221], v[4:7]
	v_mfma_f32_16x16x32_bf16 v[16:19], v[162:165], v[218:221], v[16:19]
	v_mfma_f32_16x16x32_bf16 v[16:19], v[158:161], v[214:217], v[16:19]
	v_mfma_f32_16x16x32_bf16 v[12:15], v[174:177], v[214:217], v[12:15]
	v_mfma_f32_16x16x32_bf16 v[12:15], v[178:181], v[218:221], v[12:15]
	v_mfma_f32_16x16x32_bf16 v[8:11], v[186:189], v[218:221], v[8:11]
	v_mfma_f32_16x16x32_bf16 v[8:11], v[182:185], v[214:217], v[8:11]
	v_mfma_f32_16x16x32_bf16 v[24:27], v[182:185], v[206:209], v[24:27]
	v_mfma_f32_16x16x32_bf16 v[24:27], v[186:189], v[210:213], v[24:27]
	v_mfma_f32_16x16x32_bf16 v[28:31], v[178:181], v[210:213], v[28:31]
	v_mfma_f32_16x16x32_bf16 v[28:31], v[174:177], v[206:209], v[28:31]
	v_mfma_f32_16x16x32_bf16 v[44:47], v[174:177], v[198:201], v[44:47]
	v_mfma_f32_16x16x32_bf16 v[44:47], v[178:181], v[202:205], v[44:47]
	v_mfma_f32_16x16x32_bf16 v[40:43], v[186:189], v[202:205], v[40:43]
	v_mfma_f32_16x16x32_bf16 v[40:43], v[182:185], v[198:201], v[40:43]
	v_mfma_f32_16x16x32_bf16 v[56:59], v[182:185], v[190:193], v[56:59]
	v_mfma_f32_16x16x32_bf16 v[56:59], v[186:189], v[194:197], v[56:59]
	v_mfma_f32_16x16x32_bf16 v[60:63], v[178:181], v[194:197], v[60:63]
	v_mfma_f32_16x16x32_bf16 v[60:63], v[174:177], v[190:193], v[60:63]
	s_barrier
	s_add_i32 s14, 0, 0x18000
	v_add_u32_e32 v1, s14, v151
	s_add_i32 s64, 0, 0x1c000
	ds_read_b128 v[158:161], v1
	ds_read_b128 v[162:165], v1 offset:1024
	ds_read_b128 v[166:169], v1 offset:2048
	ds_read_b128 v[170:173], v1 offset:3072
	v_add_u32_e32 v1, s64, v151
	ds_read_b128 v[174:177], v1
	ds_read_b128 v[178:181], v1 offset:1024
	ds_read_b128 v[182:185], v1 offset:2048
	ds_read_b128 v[186:189], v1 offset:3072
	s_add_u32 s12, s22, 0x2b0000
	s_addc_u32 s13, s23, 0
	s_mov_b32 m0, s20
	v_lshl_add_u64 v[224:225], s[12:13], 0, v[132:133]
	ds_read_b128 v[190:193], v155 offset:32768
	ds_read_b128 v[194:197], v155 offset:33792
	ds_read_b128 v[198:201], v155 offset:34816
	ds_read_b128 v[202:205], v155 offset:35840
	ds_read_b128 v[206:209], v155 offset:36864
	ds_read_b128 v[210:213], v155 offset:37888
	ds_read_b128 v[214:217], v155 offset:38912
	ds_read_b128 v[218:221], v155 offset:39936
	global_load_lds_dwordx4 v[224:225], off
	s_mov_b32 m0, s21
	v_lshl_add_u64 v[224:225], s[12:13], 0, v[136:137]
	global_load_lds_dwordx4 v[224:225], off
	s_waitcnt vmcnt(8) lgkmcnt(0)
	s_barrier
	v_mfma_f32_16x16x32_bf16 v[128:131], v[158:161], v[190:193], v[128:131]
	v_mfma_f32_16x16x32_bf16 v[128:131], v[162:165], v[194:197], v[128:131]
	v_mfma_f32_16x16x32_bf16 v[116:119], v[170:173], v[194:197], v[116:119]
	v_mfma_f32_16x16x32_bf16 v[116:119], v[166:169], v[190:193], v[116:119]
	v_mfma_f32_16x16x32_bf16 v[100:103], v[166:169], v[198:201], v[100:103]
	v_mfma_f32_16x16x32_bf16 v[100:103], v[170:173], v[202:205], v[100:103]
	v_mfma_f32_16x16x32_bf16 v[112:115], v[162:165], v[202:205], v[112:115]
	v_mfma_f32_16x16x32_bf16 v[112:115], v[158:161], v[198:201], v[112:115]
	v_mfma_f32_16x16x32_bf16 v[96:99], v[158:161], v[206:209], v[96:99]
	v_mfma_f32_16x16x32_bf16 v[96:99], v[162:165], v[210:213], v[96:99]
	v_mfma_f32_16x16x32_bf16 v[84:87], v[170:173], v[210:213], v[84:87]
	v_mfma_f32_16x16x32_bf16 v[84:87], v[166:169], v[206:209], v[84:87]
	v_mfma_f32_16x16x32_bf16 v[64:67], v[166:169], v[214:217], v[64:67]
	v_mfma_f32_16x16x32_bf16 v[64:67], v[170:173], v[218:221], v[64:67]
	v_mfma_f32_16x16x32_bf16 v[80:83], v[162:165], v[218:221], v[80:83]
	v_mfma_f32_16x16x32_bf16 v[80:83], v[158:161], v[214:217], v[80:83]
	v_mfma_f32_16x16x32_bf16 v[72:75], v[174:177], v[214:217], v[72:75]
	v_mfma_f32_16x16x32_bf16 v[72:75], v[178:181], v[218:221], v[72:75]
	v_mfma_f32_16x16x32_bf16 v[68:71], v[186:189], v[218:221], v[68:71]
	v_mfma_f32_16x16x32_bf16 v[68:71], v[182:185], v[214:217], v[68:71]
	v_mfma_f32_16x16x32_bf16 v[88:91], v[182:185], v[206:209], v[88:91]
	v_mfma_f32_16x16x32_bf16 v[88:91], v[186:189], v[210:213], v[88:91]
	v_mfma_f32_16x16x32_bf16 v[92:95], v[178:181], v[210:213], v[92:95]
	v_mfma_f32_16x16x32_bf16 v[92:95], v[174:177], v[206:209], v[92:95]
	v_mfma_f32_16x16x32_bf16 v[108:111], v[174:177], v[198:201], v[108:111]
	v_mfma_f32_16x16x32_bf16 v[108:111], v[178:181], v[202:205], v[108:111]
	v_mfma_f32_16x16x32_bf16 v[104:107], v[186:189], v[202:205], v[104:107]
	v_mfma_f32_16x16x32_bf16 v[104:107], v[182:185], v[198:201], v[104:107]
	v_mfma_f32_16x16x32_bf16 v[120:123], v[182:185], v[190:193], v[120:123]
	v_mfma_f32_16x16x32_bf16 v[120:123], v[186:189], v[194:197], v[120:123]
	v_mfma_f32_16x16x32_bf16 v[124:127], v[178:181], v[194:197], v[124:127]
	v_mfma_f32_16x16x32_bf16 v[124:127], v[174:177], v[190:193], v[124:127]
	s_barrier
	s_add_u32 s12, s48, 0x8000
	s_addc_u32 s13, s49, 0
	s_add_i32 s14, s14, s17
	v_lshl_add_u64 v[224:225], s[12:13], 0, v[134:135]
	s_mov_b32 m0, s14
	ds_read_b128 v[190:193], v155 offset:49152
	ds_read_b128 v[194:197], v155 offset:50176
	ds_read_b128 v[198:201], v155 offset:51200
	ds_read_b128 v[202:205], v155 offset:52224
	ds_read_b128 v[206:209], v155 offset:53248
	ds_read_b128 v[210:213], v155 offset:54272
	ds_read_b128 v[214:217], v155 offset:55296
	ds_read_b128 v[218:221], v155 offset:56320
	global_load_lds_dwordx4 v[224:225], off
	s_add_i32 m0, s14, 0x2000
	v_lshl_add_u64 v[224:225], s[12:13], 0, v[138:139]
	s_add_u32 s12, s48, 0xc000
	s_addc_u32 s13, s49, 0
	s_add_i32 s14, s64, s17
	global_load_lds_dwordx4 v[224:225], off
	v_lshl_add_u64 v[224:225], s[12:13], 0, v[134:135]
	s_mov_b32 m0, s14
	v_lshl_add_u64 v[144:145], v[144:145], 0, s[36:37]
	global_load_lds_dwordx4 v[224:225], off
	s_add_i32 m0, s14, 0x2000
	v_lshl_add_u64 v[224:225], s[12:13], 0, v[138:139]
	global_load_lds_dwordx4 v[224:225], off
	s_mov_b32 m0, s25
	s_nop 0
	global_load_lds_dwordx4 v[144:145], off
	s_mov_b32 m0, s33
	v_lshl_add_u64 v[144:145], v[222:223], 0, s[36:37]
	global_load_lds_dwordx4 v[144:145], off
	s_waitcnt vmcnt(8) lgkmcnt(0)
	s_barrier
	v_mfma_f32_16x16x32_bf16 v[76:79], v[158:161], v[190:193], v[76:79]
	v_mfma_f32_16x16x32_bf16 v[76:79], v[162:165], v[194:197], v[76:79]
	v_mfma_f32_16x16x32_bf16 v[52:55], v[170:173], v[194:197], v[52:55]
	v_mfma_f32_16x16x32_bf16 v[52:55], v[166:169], v[190:193], v[52:55]
	v_mfma_f32_16x16x32_bf16 v[36:39], v[166:169], v[198:201], v[36:39]
	v_mfma_f32_16x16x32_bf16 v[36:39], v[170:173], v[202:205], v[36:39]
	v_mfma_f32_16x16x32_bf16 v[48:51], v[162:165], v[202:205], v[48:51]
	v_mfma_f32_16x16x32_bf16 v[48:51], v[158:161], v[198:201], v[48:51]
	v_mfma_f32_16x16x32_bf16 v[32:35], v[158:161], v[206:209], v[32:35]
	v_mfma_f32_16x16x32_bf16 v[32:35], v[162:165], v[210:213], v[32:35]
	v_mfma_f32_16x16x32_bf16 v[20:23], v[170:173], v[210:213], v[20:23]
	v_mfma_f32_16x16x32_bf16 v[20:23], v[166:169], v[206:209], v[20:23]
	v_mfma_f32_16x16x32_bf16 v[4:7], v[166:169], v[214:217], v[4:7]
	v_mfma_f32_16x16x32_bf16 v[4:7], v[170:173], v[218:221], v[4:7]
	v_mfma_f32_16x16x32_bf16 v[16:19], v[162:165], v[218:221], v[16:19]
	v_mfma_f32_16x16x32_bf16 v[16:19], v[158:161], v[214:217], v[16:19]
	v_mfma_f32_16x16x32_bf16 v[12:15], v[174:177], v[214:217], v[12:15]
	v_mfma_f32_16x16x32_bf16 v[12:15], v[178:181], v[218:221], v[12:15]
	v_mfma_f32_16x16x32_bf16 v[8:11], v[186:189], v[218:221], v[8:11]
	v_mfma_f32_16x16x32_bf16 v[8:11], v[182:185], v[214:217], v[8:11]
	v_mfma_f32_16x16x32_bf16 v[24:27], v[182:185], v[206:209], v[24:27]
	v_mfma_f32_16x16x32_bf16 v[24:27], v[186:189], v[210:213], v[24:27]
	v_mfma_f32_16x16x32_bf16 v[28:31], v[178:181], v[210:213], v[28:31]
	v_mfma_f32_16x16x32_bf16 v[28:31], v[174:177], v[206:209], v[28:31]
	v_mfma_f32_16x16x32_bf16 v[44:47], v[174:177], v[198:201], v[44:47]
	v_mfma_f32_16x16x32_bf16 v[44:47], v[178:181], v[202:205], v[44:47]
	v_mfma_f32_16x16x32_bf16 v[40:43], v[186:189], v[202:205], v[40:43]
	v_mfma_f32_16x16x32_bf16 v[40:43], v[182:185], v[198:201], v[40:43]
	v_mfma_f32_16x16x32_bf16 v[56:59], v[182:185], v[190:193], v[56:59]
	v_mfma_f32_16x16x32_bf16 v[56:59], v[186:189], v[194:197], v[56:59]
	v_mfma_f32_16x16x32_bf16 v[60:63], v[178:181], v[194:197], v[60:63]
	v_mfma_f32_16x16x32_bf16 v[60:63], v[174:177], v[190:193], v[60:63]
	s_barrier
	s_add_i32 s0, s0, 2
	s_add_u32 s1, s1, 0x10000
	s_addc_u32 s59, s59, 0
	s_add_u32 s60, s60, 0x100
	s_addc_u32 s61, s61, 0
	s_add_u32 s46, s46, 0xffffff00
	s_addc_u32 s47, s47, -1
	v_lshl_add_u64 v[2:3], v[2:3], 0, s[40:41]
	s_cmpk_gt_u32 s0, 0xa9
	v_lshl_add_u64 v[148:149], v[148:149], 0, s[40:41]
	s_cbranch_scc0 .LBB0_896
	s_and_b64 vcc, exec, s[38:39]
	s_cbranch_vccz .LBB0_899
	s_barrier

.LBB0_1053:
	ds_read_b128 v[146:149], v155
	ds_read_b128 v[160:163], v155 offset:1024
	ds_read_b128 v[164:167], v155 offset:2048
	ds_read_b128 v[168:171], v155 offset:3072
	ds_read_b128 v[172:175], v156
	ds_read_b128 v[176:179], v156 offset:1024
	ds_read_b128 v[180:183], v156 offset:2048
	ds_read_b128 v[184:187], v156 offset:3072
	s_add_u32 s12, s68, s30
	s_addc_u32 s13, s69, 0
	s_cmp_eq_u32 s30, s6
	s_cselect_b32 s23, s0, s13
	s_cselect_b32 s22, s1, s12
	s_cselect_b32 s53, s41, s67
	s_cselect_b32 s52, s64, s66
	s_add_i32 s71, s21, 0xc000
	v_lshl_add_u64 v[220:221], v[2:3], 0, s[30:31]
	s_mov_b32 m0, s71
	s_add_i32 s70, s21, 0xe000
	ds_read_b128 v[188:191], v157
	ds_read_b128 v[192:195], v157 offset:1024
	ds_read_b128 v[196:199], v157 offset:2048
	ds_read_b128 v[200:203], v157 offset:3072
	ds_read_b128 v[204:207], v157 offset:4096
	ds_read_b128 v[208:211], v157 offset:5120
	ds_read_b128 v[212:215], v157 offset:6144
	ds_read_b128 v[216:219], v157 offset:7168
	global_load_lds_dwordx4 v[220:221], off
	s_mov_b32 m0, s70
	v_lshl_add_u64 v[220:221], v[150:151], 0, s[30:31]
	global_load_lds_dwordx4 v[220:221], off
	s_waitcnt vmcnt(8) lgkmcnt(0)
	s_barrier
	v_mfma_f32_16x16x32_bf16 v[128:131], v[146:149], v[188:191], v[128:131]
	v_mfma_f32_16x16x32_bf16 v[128:131], v[160:163], v[192:195], v[128:131]
	v_mfma_f32_16x16x32_bf16 v[124:127], v[168:171], v[192:195], v[124:127]
	v_mfma_f32_16x16x32_bf16 v[124:127], v[164:167], v[188:191], v[124:127]
	v_mfma_f32_16x16x32_bf16 v[108:111], v[164:167], v[196:199], v[108:111]
	v_mfma_f32_16x16x32_bf16 v[108:111], v[168:171], v[200:203], v[108:111]
	v_mfma_f32_16x16x32_bf16 v[112:115], v[160:163], v[200:203], v[112:115]
	v_mfma_f32_16x16x32_bf16 v[112:115], v[146:149], v[196:199], v[112:115]
	v_mfma_f32_16x16x32_bf16 v[96:99], v[146:149], v[204:207], v[96:99]
	v_mfma_f32_16x16x32_bf16 v[96:99], v[160:163], v[208:211], v[96:99]
	v_mfma_f32_16x16x32_bf16 v[92:95], v[168:171], v[208:211], v[92:95]
	v_mfma_f32_16x16x32_bf16 v[92:95], v[164:167], v[204:207], v[92:95]
	v_mfma_f32_16x16x32_bf16 v[76:79], v[164:167], v[212:215], v[76:79]
	v_mfma_f32_16x16x32_bf16 v[76:79], v[168:171], v[216:219], v[76:79]
	v_mfma_f32_16x16x32_bf16 v[80:83], v[160:163], v[216:219], v[80:83]
	v_mfma_f32_16x16x32_bf16 v[80:83], v[146:149], v[212:215], v[80:83]
	v_mfma_f32_16x16x32_bf16 v[64:67], v[172:175], v[212:215], v[64:67]
	v_mfma_f32_16x16x32_bf16 v[64:67], v[176:179], v[216:219], v[64:67]
	v_mfma_f32_16x16x32_bf16 v[60:63], v[184:187], v[216:219], v[60:63]
	v_mfma_f32_16x16x32_bf16 v[60:63], v[180:183], v[212:215], v[60:63]
	v_mfma_f32_16x16x32_bf16 v[84:87], v[180:183], v[204:207], v[84:87]
	v_mfma_f32_16x16x32_bf16 v[84:87], v[184:187], v[208:211], v[84:87]
	v_mfma_f32_16x16x32_bf16 v[88:91], v[176:179], v[208:211], v[88:91]
	v_mfma_f32_16x16x32_bf16 v[88:91], v[172:175], v[204:207], v[88:91]
	v_mfma_f32_16x16x32_bf16 v[104:107], v[172:175], v[196:199], v[104:107]
	v_mfma_f32_16x16x32_bf16 v[104:107], v[176:179], v[200:203], v[104:107]
	v_mfma_f32_16x16x32_bf16 v[100:103], v[184:187], v[200:203], v[100:103]
	v_mfma_f32_16x16x32_bf16 v[100:103], v[180:183], v[196:199], v[100:103]
	v_mfma_f32_16x16x32_bf16 v[116:119], v[180:183], v[188:191], v[116:119]
	v_mfma_f32_16x16x32_bf16 v[116:119], v[184:187], v[192:195], v[116:119]
	v_mfma_f32_16x16x32_bf16 v[120:123], v[176:179], v[192:195], v[120:123]
	v_mfma_f32_16x16x32_bf16 v[120:123], v[172:175], v[188:191], v[120:123]
	s_barrier
	s_add_i32 s12, s58, s20
	v_lshl_add_u64 v[220:221], s[52:53], 0, v[134:135]
	s_mov_b32 m0, s12
	ds_read_b128 v[188:191], v157 offset:16384
	ds_read_b128 v[192:195], v157 offset:17408
	ds_read_b128 v[196:199], v157 offset:18432
	ds_read_b128 v[200:203], v157 offset:19456
	ds_read_b128 v[204:207], v157 offset:20480
	ds_read_b128 v[208:211], v157 offset:21504
	ds_read_b128 v[212:215], v157 offset:22528
	ds_read_b128 v[216:219], v157 offset:23552
	global_load_lds_dwordx4 v[220:221], off
	s_add_i32 m0, s12, 0x2000
	s_add_u32 s12, s52, 0x4000
	v_lshl_add_u64 v[220:221], s[52:53], 0, v[138:139]
	s_addc_u32 s13, s53, 0
	s_add_i32 s14, s59, s20
	global_load_lds_dwordx4 v[220:221], off
	v_lshl_add_u64 v[220:221], s[12:13], 0, v[134:135]
	s_mov_b32 m0, s14
	v_lshl_add_u64 v[222:223], s[22:23], 0, v[136:137]
	global_load_lds_dwordx4 v[220:221], off
	s_add_i32 m0, s14, 0x2000
	v_lshl_add_u64 v[220:221], s[12:13], 0, v[138:139]
	global_load_lds_dwordx4 v[220:221], off
	s_mov_b32 m0, s21
	v_lshl_add_u64 v[220:221], s[22:23], 0, v[132:133]
	global_load_lds_dwordx4 v[220:221], off
	s_mov_b32 m0, s24
	s_nop 0
	global_load_lds_dwordx4 v[222:223], off
	s_waitcnt vmcnt(8) lgkmcnt(0)
	s_barrier
	v_mfma_f32_16x16x32_bf16 v[72:75], v[146:149], v[188:191], v[72:75]
	v_mfma_f32_16x16x32_bf16 v[72:75], v[160:163], v[192:195], v[72:75]
	v_mfma_f32_16x16x32_bf16 v[68:71], v[168:171], v[192:195], v[68:71]
	v_mfma_f32_16x16x32_bf16 v[68:71], v[164:167], v[188:191], v[68:71]
	v_mfma_f32_16x16x32_bf16 v[44:47], v[164:167], v[196:199], v[44:47]
	v_mfma_f32_16x16x32_bf16 v[44:47], v[168:171], v[200:203], v[44:47]
	v_mfma_f32_16x16x32_bf16 v[48:51], v[160:163], v[200:203], v[48:51]
	v_mfma_f32_16x16x32_bf16 v[48:51], v[146:149], v[196:199], v[48:51]
	v_mfma_f32_16x16x32_bf16 v[32:35], v[146:149], v[204:207], v[32:35]
	v_mfma_f32_16x16x32_bf16 v[32:35], v[160:163], v[208:211], v[32:35]
	v_mfma_f32_16x16x32_bf16 v[28:31], v[168:171], v[208:211], v[28:31]
	v_mfma_f32_16x16x32_bf16 v[28:31], v[164:167], v[204:207], v[28:31]
	v_mfma_f32_16x16x32_bf16 v[12:15], v[164:167], v[212:215], v[12:15]
	v_mfma_f32_16x16x32_bf16 v[12:15], v[168:171], v[216:219], v[12:15]
	v_mfma_f32_16x16x32_bf16 v[16:19], v[160:163], v[216:219], v[16:19]
	v_mfma_f32_16x16x32_bf16 v[16:19], v[146:149], v[212:215], v[16:19]
	v_mfma_f32_16x16x32_bf16 v[8:11], v[172:175], v[212:215], v[8:11]
	v_mfma_f32_16x16x32_bf16 v[8:11], v[176:179], v[216:219], v[8:11]
	v_mfma_f32_16x16x32_bf16 v[4:7], v[184:187], v[216:219], v[4:7]
	v_mfma_f32_16x16x32_bf16 v[4:7], v[180:183], v[212:215], v[4:7]
	v_mfma_f32_16x16x32_bf16 v[20:23], v[180:183], v[204:207], v[20:23]
	v_mfma_f32_16x16x32_bf16 v[20:23], v[184:187], v[208:211], v[20:23]
	v_mfma_f32_16x16x32_bf16 v[24:27], v[176:179], v[208:211], v[24:27]
	v_mfma_f32_16x16x32_bf16 v[24:27], v[172:175], v[204:207], v[24:27]
	v_mfma_f32_16x16x32_bf16 v[40:43], v[172:175], v[196:199], v[40:43]
	v_mfma_f32_16x16x32_bf16 v[40:43], v[176:179], v[200:203], v[40:43]
	v_mfma_f32_16x16x32_bf16 v[36:39], v[184:187], v[200:203], v[36:39]
	v_mfma_f32_16x16x32_bf16 v[36:39], v[180:183], v[196:199], v[36:39]
	v_mfma_f32_16x16x32_bf16 v[52:55], v[180:183], v[188:191], v[52:55]
	v_mfma_f32_16x16x32_bf16 v[52:55], v[184:187], v[192:195], v[52:55]
	v_mfma_f32_16x16x32_bf16 v[56:59], v[176:179], v[192:195], v[56:59]
	v_mfma_f32_16x16x32_bf16 v[56:59], v[172:175], v[188:191], v[56:59]
	s_barrier
	s_add_i32 s14, 0, 0x18000
	v_add_u32_e32 v0, s14, v154
	s_add_i32 s72, 0, 0x1c000
	ds_read_b128 v[146:149], v0
	ds_read_b128 v[160:163], v0 offset:1024
	ds_read_b128 v[164:167], v0 offset:2048
	ds_read_b128 v[168:171], v0 offset:3072
	v_add_u32_e32 v0, s72, v154
	ds_read_b128 v[172:175], v0
	ds_read_b128 v[176:179], v0 offset:1024
	ds_read_b128 v[180:183], v0 offset:2048
	ds_read_b128 v[184:187], v0 offset:3072
	s_add_u32 s12, s22, 0x100000
	s_addc_u32 s13, s23, 0
	s_mov_b32 m0, s25
	v_lshl_add_u64 v[224:225], s[12:13], 0, v[132:133]
	ds_read_b128 v[188:191], v157 offset:32768
	ds_read_b128 v[192:195], v157 offset:33792
	ds_read_b128 v[196:199], v157 offset:34816
	ds_read_b128 v[200:203], v157 offset:35840
	ds_read_b128 v[204:207], v157 offset:36864
	ds_read_b128 v[208:211], v157 offset:37888
	ds_read_b128 v[212:215], v157 offset:38912
	ds_read_b128 v[216:219], v157 offset:39936
	global_load_lds_dwordx4 v[224:225], off
	s_mov_b32 m0, s33
	v_lshl_add_u64 v[224:225], s[12:13], 0, v[136:137]
	global_load_lds_dwordx4 v[224:225], off
	s_waitcnt vmcnt(8) lgkmcnt(0)
	s_barrier
	v_mfma_f32_16x16x32_bf16 v[128:131], v[146:149], v[188:191], v[128:131]
	v_mfma_f32_16x16x32_bf16 v[128:131], v[160:163], v[192:195], v[128:131]
	v_mfma_f32_16x16x32_bf16 v[124:127], v[168:171], v[192:195], v[124:127]
	v_mfma_f32_16x16x32_bf16 v[124:127], v[164:167], v[188:191], v[124:127]
	v_mfma_f32_16x16x32_bf16 v[108:111], v[164:167], v[196:199], v[108:111]
	v_mfma_f32_16x16x32_bf16 v[108:111], v[168:171], v[200:203], v[108:111]
	v_mfma_f32_16x16x32_bf16 v[112:115], v[160:163], v[200:203], v[112:115]
	v_mfma_f32_16x16x32_bf16 v[112:115], v[146:149], v[196:199], v[112:115]
	v_mfma_f32_16x16x32_bf16 v[96:99], v[146:149], v[204:207], v[96:99]
	v_mfma_f32_16x16x32_bf16 v[96:99], v[160:163], v[208:211], v[96:99]
	v_mfma_f32_16x16x32_bf16 v[92:95], v[168:171], v[208:211], v[92:95]
	v_mfma_f32_16x16x32_bf16 v[92:95], v[164:167], v[204:207], v[92:95]
	v_mfma_f32_16x16x32_bf16 v[76:79], v[164:167], v[212:215], v[76:79]
	v_mfma_f32_16x16x32_bf16 v[76:79], v[168:171], v[216:219], v[76:79]
	v_mfma_f32_16x16x32_bf16 v[80:83], v[160:163], v[216:219], v[80:83]
	v_mfma_f32_16x16x32_bf16 v[80:83], v[146:149], v[212:215], v[80:83]
	v_mfma_f32_16x16x32_bf16 v[64:67], v[172:175], v[212:215], v[64:67]
	v_mfma_f32_16x16x32_bf16 v[64:67], v[176:179], v[216:219], v[64:67]
	v_mfma_f32_16x16x32_bf16 v[60:63], v[184:187], v[216:219], v[60:63]
	v_mfma_f32_16x16x32_bf16 v[60:63], v[180:183], v[212:215], v[60:63]
	v_mfma_f32_16x16x32_bf16 v[84:87], v[180:183], v[204:207], v[84:87]
	v_mfma_f32_16x16x32_bf16 v[84:87], v[184:187], v[208:211], v[84:87]
	v_mfma_f32_16x16x32_bf16 v[88:91], v[176:179], v[208:211], v[88:91]
	v_mfma_f32_16x16x32_bf16 v[88:91], v[172:175], v[204:207], v[88:91]
	v_mfma_f32_16x16x32_bf16 v[104:107], v[172:175], v[196:199], v[104:107]
	v_mfma_f32_16x16x32_bf16 v[104:107], v[176:179], v[200:203], v[104:107]
	v_mfma_f32_16x16x32_bf16 v[100:103], v[184:187], v[200:203], v[100:103]
	v_mfma_f32_16x16x32_bf16 v[100:103], v[180:183], v[196:199], v[100:103]
	v_mfma_f32_16x16x32_bf16 v[116:119], v[180:183], v[188:191], v[116:119]
	v_mfma_f32_16x16x32_bf16 v[116:119], v[184:187], v[192:195], v[116:119]
	v_mfma_f32_16x16x32_bf16 v[120:123], v[176:179], v[192:195], v[120:123]
	v_mfma_f32_16x16x32_bf16 v[120:123], v[172:175], v[188:191], v[120:123]
	s_barrier
	s_add_u32 s12, s52, 0x8000
	s_addc_u32 s13, s53, 0
	s_add_i32 s14, s14, s20
	v_lshl_add_u64 v[224:225], s[12:13], 0, v[134:135]
	s_mov_b32 m0, s14
	ds_read_b128 v[188:191], v157 offset:49152
	ds_read_b128 v[192:195], v157 offset:50176
	ds_read_b128 v[196:199], v157 offset:51200
	ds_read_b128 v[200:203], v157 offset:52224
	ds_read_b128 v[204:207], v157 offset:53248
	ds_read_b128 v[208:211], v157 offset:54272
	ds_read_b128 v[212:215], v157 offset:55296
	ds_read_b128 v[216:219], v157 offset:56320
	global_load_lds_dwordx4 v[224:225], off
	s_add_i32 m0, s14, 0x2000
	v_lshl_add_u64 v[224:225], s[12:13], 0, v[138:139]
	s_add_u32 s12, s52, 0xc000
	s_addc_u32 s13, s53, 0
	s_add_i32 s14, s72, s20
	global_load_lds_dwordx4 v[224:225], off
	v_lshl_add_u64 v[224:225], s[12:13], 0, v[134:135]
	s_mov_b32 m0, s14
	v_lshl_add_u64 v[220:221], v[220:221], 0, s[28:29]
	global_load_lds_dwordx4 v[224:225], off
	s_add_i32 m0, s14, 0x2000
	v_lshl_add_u64 v[224:225], s[12:13], 0, v[138:139]
	global_load_lds_dwordx4 v[224:225], off
	s_mov_b32 m0, s54
	s_nop 0
	global_load_lds_dwordx4 v[220:221], off
	s_mov_b32 m0, s55
	v_lshl_add_u64 v[220:221], v[222:223], 0, s[28:29]
	global_load_lds_dwordx4 v[220:221], off
	s_waitcnt vmcnt(8) lgkmcnt(0)
	s_barrier
	v_mfma_f32_16x16x32_bf16 v[72:75], v[146:149], v[188:191], v[72:75]
	v_mfma_f32_16x16x32_bf16 v[72:75], v[160:163], v[192:195], v[72:75]
	v_mfma_f32_16x16x32_bf16 v[68:71], v[168:171], v[192:195], v[68:71]
	v_mfma_f32_16x16x32_bf16 v[68:71], v[164:167], v[188:191], v[68:71]
	v_mfma_f32_16x16x32_bf16 v[44:47], v[164:167], v[196:199], v[44:47]
	v_mfma_f32_16x16x32_bf16 v[44:47], v[168:171], v[200:203], v[44:47]
	v_mfma_f32_16x16x32_bf16 v[48:51], v[160:163], v[200:203], v[48:51]
	v_mfma_f32_16x16x32_bf16 v[48:51], v[146:149], v[196:199], v[48:51]
	v_mfma_f32_16x16x32_bf16 v[32:35], v[146:149], v[204:207], v[32:35]
	v_mfma_f32_16x16x32_bf16 v[32:35], v[160:163], v[208:211], v[32:35]
	v_mfma_f32_16x16x32_bf16 v[28:31], v[168:171], v[208:211], v[28:31]
	v_mfma_f32_16x16x32_bf16 v[28:31], v[164:167], v[204:207], v[28:31]
	v_mfma_f32_16x16x32_bf16 v[12:15], v[164:167], v[212:215], v[12:15]
	v_mfma_f32_16x16x32_bf16 v[12:15], v[168:171], v[216:219], v[12:15]
	v_mfma_f32_16x16x32_bf16 v[16:19], v[160:163], v[216:219], v[16:19]
	v_mfma_f32_16x16x32_bf16 v[16:19], v[146:149], v[212:215], v[16:19]
	v_mfma_f32_16x16x32_bf16 v[8:11], v[172:175], v[212:215], v[8:11]
	v_mfma_f32_16x16x32_bf16 v[8:11], v[176:179], v[216:219], v[8:11]
	v_mfma_f32_16x16x32_bf16 v[4:7], v[184:187], v[216:219], v[4:7]
	v_mfma_f32_16x16x32_bf16 v[4:7], v[180:183], v[212:215], v[4:7]
	v_mfma_f32_16x16x32_bf16 v[20:23], v[180:183], v[204:207], v[20:23]
	v_mfma_f32_16x16x32_bf16 v[20:23], v[184:187], v[208:211], v[20:23]
	v_mfma_f32_16x16x32_bf16 v[24:27], v[176:179], v[208:211], v[24:27]
	v_mfma_f32_16x16x32_bf16 v[24:27], v[172:175], v[204:207], v[24:27]
	v_mfma_f32_16x16x32_bf16 v[40:43], v[172:175], v[196:199], v[40:43]
	v_mfma_f32_16x16x32_bf16 v[40:43], v[176:179], v[200:203], v[40:43]
	v_mfma_f32_16x16x32_bf16 v[36:39], v[184:187], v[200:203], v[36:39]
	v_mfma_f32_16x16x32_bf16 v[36:39], v[180:183], v[196:199], v[36:39]
	v_mfma_f32_16x16x32_bf16 v[52:55], v[180:183], v[188:191], v[52:55]
	v_mfma_f32_16x16x32_bf16 v[52:55], v[184:187], v[192:195], v[52:55]
	v_mfma_f32_16x16x32_bf16 v[56:59], v[176:179], v[192:195], v[56:59]
	v_mfma_f32_16x16x32_bf16 v[56:59], v[172:175], v[188:191], v[56:59]
	s_barrier
	s_add_i32 s65, s65, 2
	s_add_u32 s66, s66, 0x10000
	s_addc_u32 s67, s67, 0
	s_add_u32 s68, s68, 0x100
	s_addc_u32 s69, s69, 0
	s_add_u32 s6, s6, 0xffffff00
	s_addc_u32 s7, s7, -1
	v_lshl_add_u64 v[2:3], v[2:3], 0, s[36:37]
	s_cmp_gt_u32 s65, 61
	v_lshl_add_u64 v[150:151], v[150:151], 0, s[36:37]
	s_cbranch_scc0 .LBB0_1053
	s_and_b64 vcc, exec, s[34:35]
	s_cbranch_vccnz .LBB0_1061
	s_and_b64 s[0:1], s[10:11], s[4:5]
	s_andn2_b64 vcc, exec, s[0:1]
	s_cbranch_vccz .LBB0_1062

.LBB0_1734:
	ds_read_b128 v[158:161], v153
	ds_read_b128 v[162:165], v153 offset:1024
	ds_read_b128 v[166:169], v153 offset:2048
	ds_read_b128 v[170:173], v153 offset:3072
	ds_read_b128 v[174:177], v154
	ds_read_b128 v[178:181], v154 offset:1024
	ds_read_b128 v[182:185], v154 offset:2048
	ds_read_b128 v[186:189], v154 offset:3072
	s_add_u32 s12, s60, s24
	s_addc_u32 s13, s61, 0
	s_cmp_eq_u32 s24, s44
	s_cselect_b32 s23, s9, s13
	s_cselect_b32 s22, s8, s12
	s_cselect_b32 s47, s43, s59
	s_cselect_b32 s46, s42, s1
	s_add_i32 s63, s18, 0xc000
	v_lshl_add_u64 v[144:145], v[2:3], 0, s[24:25]
	s_mov_b32 m0, s63
	s_add_i32 s62, s18, 0xe000
	ds_read_b128 v[190:193], v155
	ds_read_b128 v[194:197], v155 offset:1024
	ds_read_b128 v[198:201], v155 offset:2048
	ds_read_b128 v[202:205], v155 offset:3072
	ds_read_b128 v[206:209], v155 offset:4096
	ds_read_b128 v[210:213], v155 offset:5120
	ds_read_b128 v[214:217], v155 offset:6144
	ds_read_b128 v[218:221], v155 offset:7168
	global_load_lds_dwordx4 v[144:145], off
	s_mov_b32 m0, s62
	v_lshl_add_u64 v[144:145], v[148:149], 0, s[24:25]
	global_load_lds_dwordx4 v[144:145], off
	s_waitcnt vmcnt(8) lgkmcnt(0)
	s_barrier
	v_mfma_f32_16x16x32_bf16 v[128:131], v[158:161], v[190:193], v[128:131]
	v_mfma_f32_16x16x32_bf16 v[128:131], v[162:165], v[194:197], v[128:131]
	v_mfma_f32_16x16x32_bf16 v[116:119], v[170:173], v[194:197], v[116:119]
	v_mfma_f32_16x16x32_bf16 v[116:119], v[166:169], v[190:193], v[116:119]
	v_mfma_f32_16x16x32_bf16 v[100:103], v[166:169], v[198:201], v[100:103]
	v_mfma_f32_16x16x32_bf16 v[100:103], v[170:173], v[202:205], v[100:103]
	v_mfma_f32_16x16x32_bf16 v[112:115], v[162:165], v[202:205], v[112:115]
	v_mfma_f32_16x16x32_bf16 v[112:115], v[158:161], v[198:201], v[112:115]
	v_mfma_f32_16x16x32_bf16 v[96:99], v[158:161], v[206:209], v[96:99]
	v_mfma_f32_16x16x32_bf16 v[96:99], v[162:165], v[210:213], v[96:99]
	v_mfma_f32_16x16x32_bf16 v[84:87], v[170:173], v[210:213], v[84:87]
	v_mfma_f32_16x16x32_bf16 v[84:87], v[166:169], v[206:209], v[84:87]
	v_mfma_f32_16x16x32_bf16 v[64:67], v[166:169], v[214:217], v[64:67]
	v_mfma_f32_16x16x32_bf16 v[64:67], v[170:173], v[218:221], v[64:67]
	v_mfma_f32_16x16x32_bf16 v[80:83], v[162:165], v[218:221], v[80:83]
	v_mfma_f32_16x16x32_bf16 v[80:83], v[158:161], v[214:217], v[80:83]
	v_mfma_f32_16x16x32_bf16 v[72:75], v[174:177], v[214:217], v[72:75]
	v_mfma_f32_16x16x32_bf16 v[72:75], v[178:181], v[218:221], v[72:75]
	v_mfma_f32_16x16x32_bf16 v[68:71], v[186:189], v[218:221], v[68:71]
	v_mfma_f32_16x16x32_bf16 v[68:71], v[182:185], v[214:217], v[68:71]
	v_mfma_f32_16x16x32_bf16 v[88:91], v[182:185], v[206:209], v[88:91]
	v_mfma_f32_16x16x32_bf16 v[88:91], v[186:189], v[210:213], v[88:91]
	v_mfma_f32_16x16x32_bf16 v[92:95], v[178:181], v[210:213], v[92:95]
	v_mfma_f32_16x16x32_bf16 v[92:95], v[174:177], v[206:209], v[92:95]
	v_mfma_f32_16x16x32_bf16 v[108:111], v[174:177], v[198:201], v[108:111]
	v_mfma_f32_16x16x32_bf16 v[108:111], v[178:181], v[202:205], v[108:111]
	v_mfma_f32_16x16x32_bf16 v[104:107], v[186:189], v[202:205], v[104:107]
	v_mfma_f32_16x16x32_bf16 v[104:107], v[182:185], v[198:201], v[104:107]
	v_mfma_f32_16x16x32_bf16 v[120:123], v[182:185], v[190:193], v[120:123]
	v_mfma_f32_16x16x32_bf16 v[120:123], v[186:189], v[194:197], v[120:123]
	v_mfma_f32_16x16x32_bf16 v[124:127], v[178:181], v[194:197], v[124:127]
	v_mfma_f32_16x16x32_bf16 v[124:127], v[174:177], v[190:193], v[124:127]
	s_barrier
	s_add_i32 s12, s52, s17
	v_lshl_add_u64 v[144:145], s[46:47], 0, v[134:135]
	s_mov_b32 m0, s12
	ds_read_b128 v[190:193], v155 offset:16384
	ds_read_b128 v[194:197], v155 offset:17408
	ds_read_b128 v[198:201], v155 offset:18432
	ds_read_b128 v[202:205], v155 offset:19456
	ds_read_b128 v[206:209], v155 offset:20480
	ds_read_b128 v[210:213], v155 offset:21504
	ds_read_b128 v[214:217], v155 offset:22528
	ds_read_b128 v[218:221], v155 offset:23552
	global_load_lds_dwordx4 v[144:145], off
	s_add_i32 m0, s12, 0x2000
	s_add_u32 s12, s46, 0x4000
	v_lshl_add_u64 v[144:145], s[46:47], 0, v[138:139]
	s_addc_u32 s13, s47, 0
	s_add_i32 s14, s53, s17
	global_load_lds_dwordx4 v[144:145], off
	v_lshl_add_u64 v[144:145], s[12:13], 0, v[134:135]
	s_mov_b32 m0, s14
	v_lshl_add_u64 v[222:223], s[22:23], 0, v[136:137]
	global_load_lds_dwordx4 v[144:145], off
	s_add_i32 m0, s14, 0x2000
	v_lshl_add_u64 v[144:145], s[12:13], 0, v[138:139]
	global_load_lds_dwordx4 v[144:145], off
	s_mov_b32 m0, s18
	v_lshl_add_u64 v[144:145], s[22:23], 0, v[132:133]
	global_load_lds_dwordx4 v[144:145], off
	s_mov_b32 m0, s19
	s_nop 0
	global_load_lds_dwordx4 v[222:223], off
	s_waitcnt vmcnt(8) lgkmcnt(0)
	s_barrier
	v_mfma_f32_16x16x32_bf16 v[76:79], v[158:161], v[190:193], v[76:79]
	v_mfma_f32_16x16x32_bf16 v[76:79], v[162:165], v[194:197], v[76:79]
	v_mfma_f32_16x16x32_bf16 v[52:55], v[170:173], v[194:197], v[52:55]
	v_mfma_f32_16x16x32_bf16 v[52:55], v[166:169], v[190:193], v[52:55]
	v_mfma_f32_16x16x32_bf16 v[36:39], v[166:169], v[198:201], v[36:39]
	v_mfma_f32_16x16x32_bf16 v[36:39], v[170:173], v[202:205], v[36:39]
	v_mfma_f32_16x16x32_bf16 v[48:51], v[162:165], v[202:205], v[48:51]
	v_mfma_f32_16x16x32_bf16 v[48:51], v[158:161], v[198:201], v[48:51]
	v_mfma_f32_16x16x32_bf16 v[32:35], v[158:161], v[206:209], v[32:35]
	v_mfma_f32_16x16x32_bf16 v[32:35], v[162:165], v[210:213], v[32:35]
	v_mfma_f32_16x16x32_bf16 v[20:23], v[170:173], v[210:213], v[20:23]
	v_mfma_f32_16x16x32_bf16 v[20:23], v[166:169], v[206:209], v[20:23]
	v_mfma_f32_16x16x32_bf16 v[4:7], v[166:169], v[214:217], v[4:7]
	v_mfma_f32_16x16x32_bf16 v[4:7], v[170:173], v[218:221], v[4:7]
	v_mfma_f32_16x16x32_bf16 v[16:19], v[162:165], v[218:221], v[16:19]
	v_mfma_f32_16x16x32_bf16 v[16:19], v[158:161], v[214:217], v[16:19]
	v_mfma_f32_16x16x32_bf16 v[12:15], v[174:177], v[214:217], v[12:15]
	v_mfma_f32_16x16x32_bf16 v[12:15], v[178:181], v[218:221], v[12:15]
	v_mfma_f32_16x16x32_bf16 v[8:11], v[186:189], v[218:221], v[8:11]
	v_mfma_f32_16x16x32_bf16 v[8:11], v[182:185], v[214:217], v[8:11]
	v_mfma_f32_16x16x32_bf16 v[24:27], v[182:185], v[206:209], v[24:27]
	v_mfma_f32_16x16x32_bf16 v[24:27], v[186:189], v[210:213], v[24:27]
	v_mfma_f32_16x16x32_bf16 v[28:31], v[178:181], v[210:213], v[28:31]
	v_mfma_f32_16x16x32_bf16 v[28:31], v[174:177], v[206:209], v[28:31]
	v_mfma_f32_16x16x32_bf16 v[44:47], v[174:177], v[198:201], v[44:47]
	v_mfma_f32_16x16x32_bf16 v[44:47], v[178:181], v[202:205], v[44:47]
	v_mfma_f32_16x16x32_bf16 v[40:43], v[186:189], v[202:205], v[40:43]
	v_mfma_f32_16x16x32_bf16 v[40:43], v[182:185], v[198:201], v[40:43]
	v_mfma_f32_16x16x32_bf16 v[56:59], v[182:185], v[190:193], v[56:59]
	v_mfma_f32_16x16x32_bf16 v[56:59], v[186:189], v[194:197], v[56:59]
	v_mfma_f32_16x16x32_bf16 v[60:63], v[178:181], v[194:197], v[60:63]
	v_mfma_f32_16x16x32_bf16 v[60:63], v[174:177], v[190:193], v[60:63]
	s_barrier
	s_add_i32 s14, 0, 0x18000
	v_add_u32_e32 v1, s14, v151
	s_add_i32 s64, 0, 0x1c000
	ds_read_b128 v[158:161], v1
	ds_read_b128 v[162:165], v1 offset:1024
	ds_read_b128 v[166:169], v1 offset:2048
	ds_read_b128 v[170:173], v1 offset:3072
	v_add_u32_e32 v1, s64, v151
	ds_read_b128 v[174:177], v1
	ds_read_b128 v[178:181], v1 offset:1024
	ds_read_b128 v[182:185], v1 offset:2048
	ds_read_b128 v[186:189], v1 offset:3072
	s_add_u32 s12, s22, 0x2b0000
	s_addc_u32 s13, s23, 0
	s_mov_b32 m0, s20
	v_lshl_add_u64 v[224:225], s[12:13], 0, v[132:133]
	ds_read_b128 v[190:193], v155 offset:32768
	ds_read_b128 v[194:197], v155 offset:33792
	ds_read_b128 v[198:201], v155 offset:34816
	ds_read_b128 v[202:205], v155 offset:35840
	ds_read_b128 v[206:209], v155 offset:36864
	ds_read_b128 v[210:213], v155 offset:37888
	ds_read_b128 v[214:217], v155 offset:38912
	ds_read_b128 v[218:221], v155 offset:39936
	global_load_lds_dwordx4 v[224:225], off
	s_mov_b32 m0, s21
	v_lshl_add_u64 v[224:225], s[12:13], 0, v[136:137]
	global_load_lds_dwordx4 v[224:225], off
	s_waitcnt vmcnt(8) lgkmcnt(0)
	s_barrier
	v_mfma_f32_16x16x32_bf16 v[128:131], v[158:161], v[190:193], v[128:131]
	v_mfma_f32_16x16x32_bf16 v[128:131], v[162:165], v[194:197], v[128:131]
	v_mfma_f32_16x16x32_bf16 v[116:119], v[170:173], v[194:197], v[116:119]
	v_mfma_f32_16x16x32_bf16 v[116:119], v[166:169], v[190:193], v[116:119]
	v_mfma_f32_16x16x32_bf16 v[100:103], v[166:169], v[198:201], v[100:103]
	v_mfma_f32_16x16x32_bf16 v[100:103], v[170:173], v[202:205], v[100:103]
	v_mfma_f32_16x16x32_bf16 v[112:115], v[162:165], v[202:205], v[112:115]
	v_mfma_f32_16x16x32_bf16 v[112:115], v[158:161], v[198:201], v[112:115]
	v_mfma_f32_16x16x32_bf16 v[96:99], v[158:161], v[206:209], v[96:99]
	v_mfma_f32_16x16x32_bf16 v[96:99], v[162:165], v[210:213], v[96:99]
	v_mfma_f32_16x16x32_bf16 v[84:87], v[170:173], v[210:213], v[84:87]
	v_mfma_f32_16x16x32_bf16 v[84:87], v[166:169], v[206:209], v[84:87]
	v_mfma_f32_16x16x32_bf16 v[64:67], v[166:169], v[214:217], v[64:67]
	v_mfma_f32_16x16x32_bf16 v[64:67], v[170:173], v[218:221], v[64:67]
	v_mfma_f32_16x16x32_bf16 v[80:83], v[162:165], v[218:221], v[80:83]
	v_mfma_f32_16x16x32_bf16 v[80:83], v[158:161], v[214:217], v[80:83]
	v_mfma_f32_16x16x32_bf16 v[72:75], v[174:177], v[214:217], v[72:75]
	v_mfma_f32_16x16x32_bf16 v[72:75], v[178:181], v[218:221], v[72:75]
	v_mfma_f32_16x16x32_bf16 v[68:71], v[186:189], v[218:221], v[68:71]
	v_mfma_f32_16x16x32_bf16 v[68:71], v[182:185], v[214:217], v[68:71]
	v_mfma_f32_16x16x32_bf16 v[88:91], v[182:185], v[206:209], v[88:91]
	v_mfma_f32_16x16x32_bf16 v[88:91], v[186:189], v[210:213], v[88:91]
	v_mfma_f32_16x16x32_bf16 v[92:95], v[178:181], v[210:213], v[92:95]
	v_mfma_f32_16x16x32_bf16 v[92:95], v[174:177], v[206:209], v[92:95]
	v_mfma_f32_16x16x32_bf16 v[108:111], v[174:177], v[198:201], v[108:111]
	v_mfma_f32_16x16x32_bf16 v[108:111], v[178:181], v[202:205], v[108:111]
	v_mfma_f32_16x16x32_bf16 v[104:107], v[186:189], v[202:205], v[104:107]
	v_mfma_f32_16x16x32_bf16 v[104:107], v[182:185], v[198:201], v[104:107]
	v_mfma_f32_16x16x32_bf16 v[120:123], v[182:185], v[190:193], v[120:123]
	v_mfma_f32_16x16x32_bf16 v[120:123], v[186:189], v[194:197], v[120:123]
	v_mfma_f32_16x16x32_bf16 v[124:127], v[178:181], v[194:197], v[124:127]
	v_mfma_f32_16x16x32_bf16 v[124:127], v[174:177], v[190:193], v[124:127]
	s_barrier
	s_add_u32 s12, s46, 0x8000
	s_addc_u32 s13, s47, 0
	s_add_i32 s14, s14, s17
	v_lshl_add_u64 v[224:225], s[12:13], 0, v[134:135]
	s_mov_b32 m0, s14
	ds_read_b128 v[190:193], v155 offset:49152
	ds_read_b128 v[194:197], v155 offset:50176
	ds_read_b128 v[198:201], v155 offset:51200
	ds_read_b128 v[202:205], v155 offset:52224
	ds_read_b128 v[206:209], v155 offset:53248
	ds_read_b128 v[210:213], v155 offset:54272
	ds_read_b128 v[214:217], v155 offset:55296
	ds_read_b128 v[218:221], v155 offset:56320
	global_load_lds_dwordx4 v[224:225], off
	s_add_i32 m0, s14, 0x2000
	v_lshl_add_u64 v[224:225], s[12:13], 0, v[138:139]
	s_add_u32 s12, s46, 0xc000
	s_addc_u32 s13, s47, 0
	s_add_i32 s14, s64, s17
	global_load_lds_dwordx4 v[224:225], off
	v_lshl_add_u64 v[224:225], s[12:13], 0, v[134:135]
	s_mov_b32 m0, s14
	v_lshl_add_u64 v[144:145], v[144:145], 0, s[34:35]
	global_load_lds_dwordx4 v[224:225], off
	s_add_i32 m0, s14, 0x2000
	v_lshl_add_u64 v[224:225], s[12:13], 0, v[138:139]
	global_load_lds_dwordx4 v[224:225], off
	s_mov_b32 m0, s48
	s_nop 0
	global_load_lds_dwordx4 v[144:145], off
	s_mov_b32 m0, s49
	v_lshl_add_u64 v[144:145], v[222:223], 0, s[34:35]
	global_load_lds_dwordx4 v[144:145], off
	s_waitcnt vmcnt(8) lgkmcnt(0)
	s_barrier
	v_mfma_f32_16x16x32_bf16 v[76:79], v[158:161], v[190:193], v[76:79]
	v_mfma_f32_16x16x32_bf16 v[76:79], v[162:165], v[194:197], v[76:79]
	v_mfma_f32_16x16x32_bf16 v[52:55], v[170:173], v[194:197], v[52:55]
	v_mfma_f32_16x16x32_bf16 v[52:55], v[166:169], v[190:193], v[52:55]
	v_mfma_f32_16x16x32_bf16 v[36:39], v[166:169], v[198:201], v[36:39]
	v_mfma_f32_16x16x32_bf16 v[36:39], v[170:173], v[202:205], v[36:39]
	v_mfma_f32_16x16x32_bf16 v[48:51], v[162:165], v[202:205], v[48:51]
	v_mfma_f32_16x16x32_bf16 v[48:51], v[158:161], v[198:201], v[48:51]
	v_mfma_f32_16x16x32_bf16 v[32:35], v[158:161], v[206:209], v[32:35]
	v_mfma_f32_16x16x32_bf16 v[32:35], v[162:165], v[210:213], v[32:35]
	v_mfma_f32_16x16x32_bf16 v[20:23], v[170:173], v[210:213], v[20:23]
	v_mfma_f32_16x16x32_bf16 v[20:23], v[166:169], v[206:209], v[20:23]
	v_mfma_f32_16x16x32_bf16 v[4:7], v[166:169], v[214:217], v[4:7]
	v_mfma_f32_16x16x32_bf16 v[4:7], v[170:173], v[218:221], v[4:7]
	v_mfma_f32_16x16x32_bf16 v[16:19], v[162:165], v[218:221], v[16:19]
	v_mfma_f32_16x16x32_bf16 v[16:19], v[158:161], v[214:217], v[16:19]
	v_mfma_f32_16x16x32_bf16 v[12:15], v[174:177], v[214:217], v[12:15]
	v_mfma_f32_16x16x32_bf16 v[12:15], v[178:181], v[218:221], v[12:15]
	v_mfma_f32_16x16x32_bf16 v[8:11], v[186:189], v[218:221], v[8:11]
	v_mfma_f32_16x16x32_bf16 v[8:11], v[182:185], v[214:217], v[8:11]
	v_mfma_f32_16x16x32_bf16 v[24:27], v[182:185], v[206:209], v[24:27]
	v_mfma_f32_16x16x32_bf16 v[24:27], v[186:189], v[210:213], v[24:27]
	v_mfma_f32_16x16x32_bf16 v[28:31], v[178:181], v[210:213], v[28:31]
	v_mfma_f32_16x16x32_bf16 v[28:31], v[174:177], v[206:209], v[28:31]
	v_mfma_f32_16x16x32_bf16 v[44:47], v[174:177], v[198:201], v[44:47]
	v_mfma_f32_16x16x32_bf16 v[44:47], v[178:181], v[202:205], v[44:47]
	v_mfma_f32_16x16x32_bf16 v[40:43], v[186:189], v[202:205], v[40:43]
	v_mfma_f32_16x16x32_bf16 v[40:43], v[182:185], v[198:201], v[40:43]
	v_mfma_f32_16x16x32_bf16 v[56:59], v[182:185], v[190:193], v[56:59]
	v_mfma_f32_16x16x32_bf16 v[56:59], v[186:189], v[194:197], v[56:59]
	v_mfma_f32_16x16x32_bf16 v[60:63], v[178:181], v[194:197], v[60:63]
	v_mfma_f32_16x16x32_bf16 v[60:63], v[174:177], v[190:193], v[60:63]
	s_barrier
	s_add_i32 s0, s0, 2
	s_add_u32 s1, s1, 0x10000
	s_addc_u32 s59, s59, 0
	s_add_u32 s60, s60, 0x100
	s_addc_u32 s61, s61, 0
	s_add_u32 s44, s44, 0xffffff00
	s_addc_u32 s45, s45, -1
	v_lshl_add_u64 v[2:3], v[2:3], 0, s[38:39]
	s_cmpk_gt_u32 s0, 0xa9
	v_lshl_add_u64 v[148:149], v[148:149], 0, s[38:39]
	s_cbranch_scc0 .LBB0_1734
	s_and_b64 vcc, exec, s[36:37]
	s_cbranch_vccz .LBB0_1737
	s_barrier
